# cache policy: P4 Q / K / V^T epilogue stores also non-temporal
# baseline (speedup 1.0000x reference)
.LBB0_573:
	s_lshl_b32 s0, s83, 8
	v_mov_b32_e32 v134, v1
	v_mov_b32_e32 v140, v144
	s_add_i32 s0, s0, s71
	v_mov_b64_e32 v[138:139], s[28:29]
	v_add_u32_e32 v142, s0, v134
	v_ashrrev_i32_e32 v143, 31, v142
	v_lshl_add_u64 v[134:135], v[142:143], 2, s[42:43]
	global_load_dword v143, v[134:135], off
	s_lshl_b32 s0, s84, 8
	s_ashr_i32 s1, s0, 31
	v_lshlrev_b32_e32 v134, 2, v140
	s_lshl_b64 s[12:13], s[0:1], 1
	v_ashrrev_i32_e32 v135, 31, v134
	v_mad_i64_i32 v[140:141], s[0:1], v142, s82, v[138:139]
	v_lshl_add_u64 v[152:153], v[140:141], 0, s[12:13]
	v_lshlrev_b64 v[140:141], 1, v[134:135]
	v_add_u32_e32 v150, 16, v142
	v_ashrrev_i32_e32 v151, 31, v150
	s_waitcnt vmcnt(0)
	v_fmamk_f32 v134, v143, 0x3b2aaaab, v149
	v_mul_f32_e32 v135, 0x4b800000, v134
	v_cmp_gt_f32_e32 vcc, s81, v134
	s_nop 1
	v_cndmask_b32_e32 v134, v134, v135, vcc
	v_rsq_f32_e32 v143, v134
	v_lshl_add_u64 v[134:135], v[152:153], 0, s[8:9]
	v_lshl_add_u64 v[152:153], v[150:151], 2, s[42:43]
	v_lshl_add_u64 v[134:135], v[134:135], 0, v[140:141]
	v_mul_f32_e32 v151, 0x45800000, v143
	v_cndmask_b32_e32 v154, v143, v151, vcc
	v_pk_mul_f32 v[116:117], v[116:117], v[154:155] op_sel_hi:[1,0]
	v_pk_mul_f32 v[114:115], v[114:115], v[154:155] op_sel_hi:[1,0]
	v_pk_mul_f32 v[120:121], v[120:121], v[154:155] op_sel_hi:[1,0]
	v_pk_mul_f32 v[118:119], v[118:119], v[154:155] op_sel_hi:[1,0]
	v_pk_mul_f32 v[124:125], v[124:125], v[154:155] op_sel_hi:[1,0]
	v_pk_mul_f32 v[122:123], v[122:123], v[154:155] op_sel_hi:[1,0]
	v_pk_mul_f32 v[128:129], v[128:129], v[154:155] op_sel_hi:[1,0]
	v_pk_mul_f32 v[126:127], v[126:127], v[154:155] op_sel_hi:[1,0]
	v_cvt_pk_bf16_f32 v114, v114, v115
	v_cvt_pk_bf16_f32 v115, v116, v117
	v_cvt_pk_bf16_f32 v116, v118, v119
	v_cvt_pk_bf16_f32 v117, v120, v121
	v_cvt_pk_bf16_f32 v118, v122, v123
	v_cvt_pk_bf16_f32 v119, v124, v125
	v_cvt_pk_bf16_f32 v120, v126, v127
	v_cvt_pk_bf16_f32 v121, v128, v129
	global_store_dwordx2 v[134:135], v[114:115], off nt
	global_store_dwordx2 v[134:135], v[116:117], off offset:32 nt
	global_store_dwordx2 v[134:135], v[118:119], off offset:256 nt
	global_store_dwordx2 v[134:135], v[120:121], off offset:288 nt
	global_load_dword v118, v[152:153], off
	v_add_u32_e32 v114, 32, v142
	v_ashrrev_i32_e32 v115, 31, v114
	v_mad_i64_i32 v[116:117], s[0:1], v150, s82, v[138:139]
	v_lshl_add_u64 v[116:117], v[116:117], 0, s[12:13]
	v_lshl_add_u64 v[116:117], v[116:117], 0, s[8:9]
	v_lshl_add_u64 v[116:117], v[116:117], 0, v[140:141]
	s_waitcnt vmcnt(0)
	v_fmamk_f32 v118, v118, 0x3b2aaaab, v149
	v_mul_f32_e32 v119, 0x4b800000, v118
	v_cmp_gt_f32_e32 vcc, s81, v118
	s_nop 1
	v_cndmask_b32_e32 v118, v118, v119, vcc
	v_rsq_f32_e32 v120, v118
	v_lshl_add_u64 v[118:119], v[114:115], 2, s[42:43]
	v_mul_f32_e32 v115, 0x45800000, v120
	v_cndmask_b32_e32 v120, v120, v115, vcc
	v_pk_mul_f32 v[100:101], v[100:101], v[120:121] op_sel_hi:[1,0]
	v_pk_mul_f32 v[98:99], v[98:99], v[120:121] op_sel_hi:[1,0]
	v_pk_mul_f32 v[104:105], v[104:105], v[120:121] op_sel_hi:[1,0]
	v_pk_mul_f32 v[102:103], v[102:103], v[120:121] op_sel_hi:[1,0]
	v_pk_mul_f32 v[108:109], v[108:109], v[120:121] op_sel_hi:[1,0]
	v_pk_mul_f32 v[106:107], v[106:107], v[120:121] op_sel_hi:[1,0]
	v_pk_mul_f32 v[112:113], v[112:113], v[120:121] op_sel_hi:[1,0]
	v_pk_mul_f32 v[110:111], v[110:111], v[120:121] op_sel_hi:[1,0]
	v_cvt_pk_bf16_f32 v98, v98, v99
	v_cvt_pk_bf16_f32 v99, v100, v101
	v_cvt_pk_bf16_f32 v100, v102, v103
	v_cvt_pk_bf16_f32 v101, v104, v105
	v_cvt_pk_bf16_f32 v102, v106, v107
	v_cvt_pk_bf16_f32 v103, v108, v109
	v_cvt_pk_bf16_f32 v104, v110, v111
	v_cvt_pk_bf16_f32 v105, v112, v113
	global_store_dwordx2 v[116:117], v[98:99], off nt
	global_store_dwordx2 v[116:117], v[100:101], off offset:32 nt
	global_store_dwordx2 v[116:117], v[102:103], off offset:256 nt
	global_store_dwordx2 v[116:117], v[104:105], off offset:288 nt
	global_load_dword v102, v[118:119], off
	v_add_u32_e32 v98, 48, v142
	v_ashrrev_i32_e32 v99, 31, v98
	v_mad_i64_i32 v[100:101], s[0:1], v114, s82, v[138:139]
	v_lshl_add_u64 v[100:101], v[100:101], 0, s[12:13]
	v_lshl_add_u64 v[100:101], v[100:101], 0, s[8:9]
	v_lshl_add_u64 v[100:101], v[100:101], 0, v[140:141]
	s_waitcnt vmcnt(0)
	v_fmamk_f32 v102, v102, 0x3b2aaaab, v149
	v_mul_f32_e32 v103, 0x4b800000, v102
	v_cmp_gt_f32_e32 vcc, s81, v102
	s_nop 1
	v_cndmask_b32_e32 v102, v102, v103, vcc
	v_rsq_f32_e32 v104, v102
	v_lshl_add_u64 v[102:103], v[98:99], 2, s[42:43]
	v_mul_f32_e32 v99, 0x45800000, v104
	v_cndmask_b32_e32 v104, v104, v99, vcc
	v_pk_mul_f32 v[84:85], v[84:85], v[104:105] op_sel_hi:[1,0]
	v_pk_mul_f32 v[82:83], v[82:83], v[104:105] op_sel_hi:[1,0]
	v_pk_mul_f32 v[88:89], v[88:89], v[104:105] op_sel_hi:[1,0]
	v_pk_mul_f32 v[86:87], v[86:87], v[104:105] op_sel_hi:[1,0]
	v_pk_mul_f32 v[92:93], v[92:93], v[104:105] op_sel_hi:[1,0]
	v_pk_mul_f32 v[90:91], v[90:91], v[104:105] op_sel_hi:[1,0]
	v_pk_mul_f32 v[96:97], v[96:97], v[104:105] op_sel_hi:[1,0]
	v_pk_mul_f32 v[94:95], v[94:95], v[104:105] op_sel_hi:[1,0]
	v_cvt_pk_bf16_f32 v82, v82, v83
	v_cvt_pk_bf16_f32 v83, v84, v85
	v_cvt_pk_bf16_f32 v84, v86, v87
	v_cvt_pk_bf16_f32 v85, v88, v89
	v_cvt_pk_bf16_f32 v86, v90, v91
	v_cvt_pk_bf16_f32 v87, v92, v93
	v_cvt_pk_bf16_f32 v88, v94, v95
	v_cvt_pk_bf16_f32 v89, v96, v97
	global_store_dwordx2 v[100:101], v[82:83], off nt
	global_store_dwordx2 v[100:101], v[84:85], off offset:32 nt
	global_store_dwordx2 v[100:101], v[86:87], off offset:256 nt
	global_store_dwordx2 v[100:101], v[88:89], off offset:288 nt
	global_load_dword v86, v[102:103], off
	v_add_u32_e32 v82, 0x80, v142
	v_ashrrev_i32_e32 v83, 31, v82
	v_mad_i64_i32 v[84:85], s[0:1], v98, s82, v[138:139]
	v_lshl_add_u64 v[84:85], v[84:85], 0, s[12:13]
	v_lshl_add_u64 v[84:85], v[84:85], 0, s[8:9]
	v_lshl_add_u64 v[84:85], v[84:85], 0, v[140:141]
	s_waitcnt vmcnt(0)
	v_fmamk_f32 v86, v86, 0x3b2aaaab, v149
	v_mul_f32_e32 v87, 0x4b800000, v86
	v_cmp_gt_f32_e32 vcc, s81, v86
	s_nop 1
	v_cndmask_b32_e32 v86, v86, v87, vcc
	v_rsq_f32_e32 v88, v86
	v_lshl_add_u64 v[86:87], v[82:83], 2, s[42:43]
	v_mul_f32_e32 v83, 0x45800000, v88
	v_cndmask_b32_e32 v88, v88, v83, vcc
	v_pk_mul_f32 v[68:69], v[68:69], v[88:89] op_sel_hi:[1,0]
	v_pk_mul_f32 v[66:67], v[66:67], v[88:89] op_sel_hi:[1,0]
	v_pk_mul_f32 v[72:73], v[72:73], v[88:89] op_sel_hi:[1,0]
	v_pk_mul_f32 v[70:71], v[70:71], v[88:89] op_sel_hi:[1,0]
	v_pk_mul_f32 v[76:77], v[76:77], v[88:89] op_sel_hi:[1,0]
	v_pk_mul_f32 v[74:75], v[74:75], v[88:89] op_sel_hi:[1,0]
	v_pk_mul_f32 v[80:81], v[80:81], v[88:89] op_sel_hi:[1,0]
	v_pk_mul_f32 v[78:79], v[78:79], v[88:89] op_sel_hi:[1,0]
	v_cvt_pk_bf16_f32 v66, v66, v67
	v_cvt_pk_bf16_f32 v67, v68, v69
	v_cvt_pk_bf16_f32 v68, v70, v71
	v_cvt_pk_bf16_f32 v69, v72, v73
	v_cvt_pk_bf16_f32 v70, v74, v75
	v_cvt_pk_bf16_f32 v71, v76, v77
	v_cvt_pk_bf16_f32 v72, v78, v79
	v_cvt_pk_bf16_f32 v73, v80, v81
	global_store_dwordx2 v[84:85], v[66:67], off nt
	global_store_dwordx2 v[84:85], v[68:69], off offset:32 nt
	global_store_dwordx2 v[84:85], v[70:71], off offset:256 nt
	global_store_dwordx2 v[84:85], v[72:73], off offset:288 nt
	global_load_dword v70, v[86:87], off
	v_add_u32_e32 v66, 0x90, v142
	v_ashrrev_i32_e32 v67, 31, v66
	v_mad_i64_i32 v[68:69], s[0:1], v82, s82, v[138:139]
	v_lshl_add_u64 v[68:69], v[68:69], 0, s[12:13]
	v_lshl_add_u64 v[68:69], v[68:69], 0, s[8:9]
	v_lshl_add_u64 v[68:69], v[68:69], 0, v[140:141]
	s_waitcnt vmcnt(0)
	v_fmamk_f32 v70, v70, 0x3b2aaaab, v149
	v_mul_f32_e32 v71, 0x4b800000, v70
	v_cmp_gt_f32_e32 vcc, s81, v70
	s_nop 1
	v_cndmask_b32_e32 v70, v70, v71, vcc
	v_rsq_f32_e32 v72, v70
	v_lshl_add_u64 v[70:71], v[66:67], 2, s[42:43]
	v_mul_f32_e32 v67, 0x45800000, v72
	v_cndmask_b32_e32 v72, v72, v67, vcc
	v_pk_mul_f32 v[52:53], v[52:53], v[72:73] op_sel_hi:[1,0]
	v_pk_mul_f32 v[50:51], v[50:51], v[72:73] op_sel_hi:[1,0]
	v_pk_mul_f32 v[56:57], v[56:57], v[72:73] op_sel_hi:[1,0]
	v_pk_mul_f32 v[54:55], v[54:55], v[72:73] op_sel_hi:[1,0]
	v_pk_mul_f32 v[60:61], v[60:61], v[72:73] op_sel_hi:[1,0]
	v_pk_mul_f32 v[58:59], v[58:59], v[72:73] op_sel_hi:[1,0]
	v_pk_mul_f32 v[64:65], v[64:65], v[72:73] op_sel_hi:[1,0]
	v_pk_mul_f32 v[62:63], v[62:63], v[72:73] op_sel_hi:[1,0]
	v_cvt_pk_bf16_f32 v50, v50, v51
	v_cvt_pk_bf16_f32 v51, v52, v53
	v_cvt_pk_bf16_f32 v52, v54, v55
	v_cvt_pk_bf16_f32 v53, v56, v57
	v_cvt_pk_bf16_f32 v54, v58, v59
	v_cvt_pk_bf16_f32 v55, v60, v61
	v_cvt_pk_bf16_f32 v56, v62, v63
	v_cvt_pk_bf16_f32 v57, v64, v65
	global_store_dwordx2 v[68:69], v[50:51], off nt
	global_store_dwordx2 v[68:69], v[52:53], off offset:32 nt
	global_store_dwordx2 v[68:69], v[54:55], off offset:256 nt
	global_store_dwordx2 v[68:69], v[56:57], off offset:288 nt
	global_load_dword v54, v[70:71], off
	v_add_u32_e32 v50, 0xa0, v142
	v_ashrrev_i32_e32 v51, 31, v50
	v_mad_i64_i32 v[52:53], s[0:1], v66, s82, v[138:139]
	v_lshl_add_u64 v[52:53], v[52:53], 0, s[12:13]
	v_lshl_add_u64 v[52:53], v[52:53], 0, s[8:9]
	v_lshl_add_u64 v[52:53], v[52:53], 0, v[140:141]
	s_waitcnt vmcnt(0)
	v_fmamk_f32 v54, v54, 0x3b2aaaab, v149
	v_mul_f32_e32 v55, 0x4b800000, v54
	v_cmp_gt_f32_e32 vcc, s81, v54
	s_nop 1
	v_cndmask_b32_e32 v54, v54, v55, vcc
	v_rsq_f32_e32 v56, v54
	v_lshl_add_u64 v[54:55], v[50:51], 2, s[42:43]
	v_mul_f32_e32 v51, 0x45800000, v56
	v_cndmask_b32_e32 v56, v56, v51, vcc
	v_pk_mul_f32 v[36:37], v[36:37], v[56:57] op_sel_hi:[1,0]
	v_pk_mul_f32 v[34:35], v[34:35], v[56:57] op_sel_hi:[1,0]
	v_pk_mul_f32 v[40:41], v[40:41], v[56:57] op_sel_hi:[1,0]
	v_pk_mul_f32 v[38:39], v[38:39], v[56:57] op_sel_hi:[1,0]
	v_pk_mul_f32 v[44:45], v[44:45], v[56:57] op_sel_hi:[1,0]
	v_pk_mul_f32 v[42:43], v[42:43], v[56:57] op_sel_hi:[1,0]
	v_pk_mul_f32 v[48:49], v[48:49], v[56:57] op_sel_hi:[1,0]
	v_pk_mul_f32 v[46:47], v[46:47], v[56:57] op_sel_hi:[1,0]
	v_cvt_pk_bf16_f32 v34, v34, v35
	v_cvt_pk_bf16_f32 v35, v36, v37
	v_cvt_pk_bf16_f32 v36, v38, v39
	v_cvt_pk_bf16_f32 v37, v40, v41
	v_cvt_pk_bf16_f32 v38, v42, v43
	v_cvt_pk_bf16_f32 v39, v44, v45
	v_cvt_pk_bf16_f32 v40, v46, v47
	v_cvt_pk_bf16_f32 v41, v48, v49
	global_store_dwordx2 v[52:53], v[34:35], off nt
	global_store_dwordx2 v[52:53], v[36:37], off offset:32 nt
	global_store_dwordx2 v[52:53], v[38:39], off offset:256 nt
	global_store_dwordx2 v[52:53], v[40:41], off offset:288 nt
	global_load_dword v38, v[54:55], off
	v_add_u32_e32 v34, 0xb0, v142
	v_ashrrev_i32_e32 v35, 31, v34
	v_mad_i64_i32 v[36:37], s[0:1], v50, s82, v[138:139]
	v_lshl_add_u64 v[36:37], v[36:37], 0, s[12:13]
	v_lshl_add_u64 v[36:37], v[36:37], 0, s[8:9]
	v_lshl_add_u64 v[36:37], v[36:37], 0, v[140:141]
	s_waitcnt vmcnt(0)
	v_fmamk_f32 v38, v38, 0x3b2aaaab, v149
	v_mul_f32_e32 v39, 0x4b800000, v38
	v_cmp_gt_f32_e32 vcc, s81, v38
	s_nop 1
	v_cndmask_b32_e32 v38, v38, v39, vcc
	v_rsq_f32_e32 v40, v38
	v_lshl_add_u64 v[38:39], v[34:35], 2, s[42:43]
	v_mul_f32_e32 v35, 0x45800000, v40
	v_cndmask_b32_e32 v40, v40, v35, vcc
	v_pk_mul_f32 v[20:21], v[20:21], v[40:41] op_sel_hi:[1,0]
	v_pk_mul_f32 v[18:19], v[18:19], v[40:41] op_sel_hi:[1,0]
	v_pk_mul_f32 v[24:25], v[24:25], v[40:41] op_sel_hi:[1,0]
	v_pk_mul_f32 v[22:23], v[22:23], v[40:41] op_sel_hi:[1,0]
	v_pk_mul_f32 v[28:29], v[28:29], v[40:41] op_sel_hi:[1,0]
	v_pk_mul_f32 v[26:27], v[26:27], v[40:41] op_sel_hi:[1,0]
	v_pk_mul_f32 v[32:33], v[32:33], v[40:41] op_sel_hi:[1,0]
	v_pk_mul_f32 v[30:31], v[30:31], v[40:41] op_sel_hi:[1,0]
	v_cvt_pk_bf16_f32 v18, v18, v19
	v_cvt_pk_bf16_f32 v19, v20, v21
	v_cvt_pk_bf16_f32 v20, v22, v23
	v_cvt_pk_bf16_f32 v21, v24, v25
	v_cvt_pk_bf16_f32 v22, v26, v27
	v_cvt_pk_bf16_f32 v23, v28, v29
	v_cvt_pk_bf16_f32 v24, v30, v31
	v_cvt_pk_bf16_f32 v25, v32, v33
	global_store_dwordx2 v[36:37], v[18:19], off nt
	global_store_dwordx2 v[36:37], v[20:21], off offset:32 nt
	global_store_dwordx2 v[36:37], v[22:23], off offset:256 nt
	global_store_dwordx2 v[36:37], v[24:25], off offset:288 nt
	global_load_dword v20, v[38:39], off
	v_mad_i64_i32 v[18:19], s[0:1], v34, s82, v[138:139]
	v_lshl_add_u64 v[18:19], v[18:19], 0, s[12:13]
	v_lshl_add_u64 v[18:19], v[18:19], 0, s[8:9]
	s_and_b64 vcc, exec, s[6:7]
	v_lshl_add_u64 v[18:19], v[18:19], 0, v[140:141]
	s_waitcnt vmcnt(0)
	v_fmamk_f32 v20, v20, 0x3b2aaaab, v149
	v_mul_f32_e32 v21, 0x4b800000, v20
	v_cmp_gt_f32_e64 s[0:1], s81, v20
	s_nop 1
	v_cndmask_b32_e64 v20, v20, v21, s[0:1]
	v_rsq_f32_e32 v20, v20
	s_nop 0
	v_mul_f32_e32 v21, 0x45800000, v20
	v_cndmask_b32_e64 v20, v20, v21, s[0:1]
	v_pk_mul_f32 v[4:5], v[4:5], v[20:21] op_sel_hi:[1,0]
	v_pk_mul_f32 v[2:3], v[2:3], v[20:21] op_sel_hi:[1,0]
	v_pk_mul_f32 v[8:9], v[8:9], v[20:21] op_sel_hi:[1,0]
	v_pk_mul_f32 v[6:7], v[6:7], v[20:21] op_sel_hi:[1,0]
	v_pk_mul_f32 v[12:13], v[12:13], v[20:21] op_sel_hi:[1,0]
	v_pk_mul_f32 v[10:11], v[10:11], v[20:21] op_sel_hi:[1,0]
	v_pk_mul_f32 v[16:17], v[16:17], v[20:21] op_sel_hi:[1,0]
	v_pk_mul_f32 v[14:15], v[14:15], v[20:21] op_sel_hi:[1,0]
	v_cvt_pk_bf16_f32 v2, v2, v3
	v_cvt_pk_bf16_f32 v3, v4, v5
	s_mov_b64 s[0:1], -1
	v_cvt_pk_bf16_f32 v4, v6, v7
	v_cvt_pk_bf16_f32 v5, v8, v9
	v_cvt_pk_bf16_f32 v6, v10, v11
	v_cvt_pk_bf16_f32 v7, v12, v13
	v_cvt_pk_bf16_f32 v8, v14, v15
	v_cvt_pk_bf16_f32 v9, v16, v17
	global_store_dwordx2 v[18:19], v[2:3], off nt
	global_store_dwordx2 v[18:19], v[4:5], off offset:32 nt
	global_store_dwordx2 v[18:19], v[6:7], off offset:256 nt
	global_store_dwordx2 v[18:19], v[8:9], off offset:288 nt
	s_cbranch_vccnz .LBB0_564
	s_andn2_b64 vcc, exec, s[10:11]
	s_cbranch_vccnz .LBB0_563
	s_barrier
	s_branch .LBB0_563

.LBB0_599:
	s_lshl_b32 s12, s14, 8
	v_mov_b32_e32 v134, v1
	v_mov_b32_e32 v136, v168
	s_add_i32 s12, s12, s72
	v_mov_b64_e32 v[148:149], s[38:39]
	v_add_u32_e32 v150, s12, v134
	v_ashrrev_i32_e32 v151, 31, v150
	v_lshlrev_b32_e32 v140, 2, v136
	v_lshl_add_u64 v[136:137], v[150:151], 2, s[40:41]
	global_load_dword v165, v[136:137], off
	v_ashrrev_i32_e32 v141, 31, v140
	v_mad_i64_i32 v[136:137], s[12:13], v150, s82, v[148:149]
	v_lshlrev_b64 v[142:143], 1, v[140:141]
	v_lshl_add_u64 v[136:137], v[136:137], 0, v[142:143]
	global_load_dwordx2 v[138:139], v[136:137], off offset:512
	s_nop 0
	global_load_dwordx2 v[136:137], v[136:137], off offset:544
	s_lshl_b32 s12, s15, 2
	v_and_b32_e32 v157, 64, v173
	v_pk_mul_f32 v[152:153], v[128:129], v[128:129]
	v_xor_b32_e32 v145, 16, v173
	s_or_b32 s62, s12, s71
	v_add_u32_e32 v153, 64, v157
	v_readlane_b32 s8, v255, 2
	v_mul_f32_e32 v134, v119, v119
	v_mul_f32_e32 v144, v123, v123
	v_cmp_lt_i32_e32 vcc, v145, v153
	v_readlane_b32 s22, v255, 16
	v_readlane_b32 s23, v255, 17
	v_pk_fma_f32 v[158:159], v[118:119], v[118:119], v[134:135] op_sel_hi:[1,1,0]
	v_pk_fma_f32 v[160:161], v[122:123], v[122:123], v[144:145] op_sel_hi:[1,1,0]
	v_cndmask_b32_e32 v134, v173, v145, vcc
	v_lshl_add_u64 v[144:145], v[140:141], 2, s[22:23]
	global_load_dwordx4 v[180:183], v[144:145], off
	v_pk_mul_f32 v[154:155], v[126:127], v[126:127]
	v_xor_b32_e32 v162, 32, v173
	v_mul_f32_e32 v154, v121, v121
	v_fmac_f32_e32 v155, v126, v126
	v_pk_fma_f32 v[192:193], v[120:121], v[120:121], v[158:159]
	v_cmp_lt_i32_e32 vcc, v162, v153
	v_add_f32_e32 v190, v152, v155
	v_lshlrev_b32_e32 v178, 2, v134
	v_pk_add_f32 v[154:155], v[154:155], v[192:193] op_sel_hi:[0,1]
	v_cndmask_b32_e32 v153, v173, v162, vcc
	v_add_u32_e32 v162, 16, v150
	v_ashrrev_i32_e32 v163, 31, v162
	v_mov_b32_e32 v164, v115
	v_lshl_add_u64 v[192:193], v[162:163], 2, s[40:41]
	v_mov_b32_e32 v166, v114
	v_mov_b32_e32 v188, v129
	v_mul_f32_e32 v156, v125, v125
	v_pk_fma_f32 v[160:161], v[124:125], v[124:125], v[160:161]
	global_load_dword v179, v[192:193], off
	v_mov_b32_e32 v184, v116
	v_pk_add_f32 v[156:157], v[156:157], v[160:161] op_sel_hi:[0,1]
	v_mov_b32_e32 v186, v117
	s_ashr_i32 s63, s62, 31
	v_lshlrev_b32_e32 v177, 2, v153
	v_add_u32_e32 v158, 32, v150
	v_readlane_b32 s12, v255, 6
	v_readlane_b32 s13, v255, 7
	v_ashrrev_i32_e32 v159, 31, v158
	v_mov_b64_e32 v[146:147], s[42:43]
	v_mad_i64_i32 v[160:161], s[12:13], v158, s82, v[148:149]
	v_add_u32_e32 v152, 48, v150
	v_lshl_add_u64 v[194:195], v[160:161], 0, v[142:143]
	v_ashrrev_i32_e32 v153, 31, v152
	v_readlane_b32 s9, v255, 3
	v_readlane_b32 s10, v255, 4
	v_readlane_b32 s11, v255, 5
	v_readlane_b32 s14, v255, 8
	v_readlane_b32 s15, v255, 9
	v_readlane_b32 s16, v255, 10
	v_readlane_b32 s17, v255, 11
	v_readlane_b32 s18, v255, 12
	v_readlane_b32 s19, v255, 13
	v_readlane_b32 s20, v255, 14
	v_readlane_b32 s21, v255, 15
	s_waitcnt vmcnt(0)
	v_fmamk_f32 v134, v165, 0x3b800000, v174
	v_mul_f32_e32 v155, 0x4b800000, v134
	v_cmp_gt_f32_e32 vcc, s83, v134
	v_and_b32_e32 v165, 0xffff0000, v138
	s_nop 0
	v_cndmask_b32_e32 v134, v134, v155, vcc
	v_rsq_f32_e32 v134, v134
	v_lshlrev_b32_e32 v185, 16, v139
	v_and_b32_e32 v187, 0xffff0000, v139
	v_and_b32_e32 v139, 0xffff0000, v136
	v_lshlrev_b32_e32 v167, 16, v138
	v_lshlrev_b32_e32 v189, 16, v136
	v_lshlrev_b32_e32 v136, 16, v137
	v_mul_f32_e32 v191, v139, v139
	v_pk_mul_f32 v[192:193], v[164:165], v[164:165]
	v_and_b32_e32 v137, 0xffff0000, v137
	v_mul_f32_e32 v155, v136, v136
	v_pk_fma_f32 v[192:193], v[166:167], v[166:167], v[192:193]
	v_pk_fma_f32 v[190:191], v[188:189], v[188:189], v[190:191]
	v_mul_f32_e32 v157, v137, v137
	v_pk_fma_f32 v[192:193], v[184:185], v[184:185], v[192:193]
	v_pk_add_f32 v[154:155], v[190:191], v[154:155]
	v_mul_f32_e32 v138, 0x45800000, v134
	v_pk_fma_f32 v[190:191], v[186:187], v[186:187], v[192:193]
	v_pk_add_f32 v[154:155], v[154:155], v[156:157]
	v_cndmask_b32_e32 v134, v134, v138, vcc
	v_pk_add_f32 v[154:155], v[190:191], v[154:155]
	v_mul_f32_e32 v138, v134, v134
	v_fmac_f32_e32 v155, v154, v138
	ds_bpermute_b32 v138, v178, v155
	v_lshl_add_u64 v[190:191], v[150:151], 3, s[62:63]
	v_lshl_add_u64 v[192:193], v[158:159], 2, s[40:41]
	global_load_dword v166, v[192:193], off
	global_load_dwordx2 v[160:161], v[194:195], off offset:512
	v_mad_u64_u32 v[192:193], s[12:13], v190, s69, v[146:147]
	s_waitcnt lgkmcnt(0)
	v_add_f32_e32 v138, v155, v138
	ds_bpermute_b32 v151, v177, v138
	v_mad_i32_i24 v193, v191, s69, v193
	v_mad_i64_i32 v[156:157], s[12:13], v152, s82, v[148:149]
	v_lshl_add_u64 v[154:155], v[152:153], 2, s[40:41]
	s_waitcnt lgkmcnt(0)
	v_add_f32_e32 v138, v138, v151
	v_fmamk_f32 v138, v138, 0x3c2aaaab, v174
	v_mul_f32_e32 v151, 0x4b800000, v138
	v_cmp_gt_f32_e32 vcc, s83, v138
	v_lshl_add_u64 v[190:191], v[192:193], 0, v[142:143]
	v_lshl_add_u64 v[196:197], v[156:157], 0, v[142:143]
	v_cndmask_b32_e32 v138, v138, v151, vcc
	v_rsq_f32_e32 v138, v138
	global_load_dword v151, v[154:155], off
	global_load_dwordx2 v[156:157], v[196:197], off offset:512
	s_nop 0
	global_load_dwordx2 v[154:155], v[196:197], off offset:544
	v_mov_b32_e32 v186, v185
	v_mul_f32_e32 v164, 0x45800000, v138
	v_cndmask_b32_e32 v184, v138, v164, vcc
	v_mul_f32_e32 v138, v134, v184
	v_pk_mul_f32 v[126:127], v[126:127], v[138:139] op_sel_hi:[1,0]
	v_pk_mul_f32 v[128:129], v[128:129], v[138:139] op_sel_hi:[1,0]
	v_pk_mul_f32 v[126:127], v[180:181], v[126:127]
	v_pk_mul_f32 v[128:129], v[182:183], v[128:129]
	v_cvt_pk_bf16_f32 v126, v126, v127
	v_cvt_pk_bf16_f32 v127, v128, v129
	global_store_dwordx2 v[190:191], v[126:127], off nt
	global_load_dwordx4 v[126:129], v[144:145], off offset:64
	v_pk_mul_f32 v[118:119], v[118:119], v[138:139] op_sel_hi:[1,0]
	v_pk_mul_f32 v[120:121], v[120:121], v[138:139] op_sel_hi:[1,0]
	v_pk_mul_f32 v[122:123], v[122:123], v[138:139] op_sel_hi:[1,0]
	v_pk_mul_f32 v[124:125], v[124:125], v[138:139] op_sel_hi:[1,0]
	v_cmp_gt_i32_e32 vcc, s70, v150
	v_pk_mul_f32 v[114:115], v[114:115], v[138:139] op_sel_hi:[1,0]
	v_pk_mul_f32 v[116:117], v[116:117], v[138:139] op_sel_hi:[1,0]
	v_mov_b32_e32 v138, v189
	v_mov_b32_e32 v164, v167
	v_pk_mul_f32 v[138:139], v[138:139], v[184:185] op_sel_hi:[1,0]
	v_pk_mul_f32 v[136:137], v[136:137], v[184:185] op_sel_hi:[1,0]
	v_pk_mul_f32 v[186:187], v[186:187], v[184:185] op_sel_hi:[1,0]
	v_pk_mul_f32 v[164:165], v[164:165], v[184:185] op_sel_hi:[1,0]
	s_waitcnt vmcnt(0)
	v_pk_mul_f32 v[120:121], v[128:129], v[120:121]
	v_pk_mul_f32 v[118:119], v[126:127], v[118:119]
	s_nop 0
	v_cvt_pk_bf16_f32 v118, v118, v119
	v_cvt_pk_bf16_f32 v119, v120, v121
	global_store_dwordx2 v[190:191], v[118:119], off offset:32 nt
	global_load_dwordx4 v[118:121], v[144:145], off offset:128
	s_waitcnt vmcnt(0)
	v_pk_mul_f32 v[120:121], v[124:125], v[120:121]
	v_pk_mul_f32 v[118:119], v[122:123], v[118:119]
	v_cndmask_b32_e32 v122, v175, v176, vcc
	v_cvt_pk_bf16_f32 v118, v118, v119
	v_cvt_pk_bf16_f32 v119, v120, v121
	global_store_dwordx2 v[190:191], v[118:119], off offset:64 nt
	global_load_dwordx4 v[118:121], v[144:145], off offset:192
	v_and_b32_e32 v122, v122, v150
	v_lshlrev_b32_e32 v134, 4, v122
	s_waitcnt vmcnt(0)
	v_pk_mul_f32 v[116:117], v[116:117], v[120:121]
	v_pk_mul_f32 v[114:115], v[114:115], v[118:119]
	s_nop 0
	v_cvt_pk_bf16_f32 v114, v114, v115
	v_cvt_pk_bf16_f32 v115, v116, v117
	global_store_dwordx2 v[190:191], v[114:115], off offset:96 nt
	v_lshl_add_u64 v[114:115], v[134:135], 0, v[140:141]
	v_lshl_add_u64 v[114:115], v[114:115], 3, s[44:45]
	global_load_dwordx4 v[116:119], v[144:145], off offset:256
	global_load_dwordx4 v[120:123], v[144:145], off offset:320
	global_load_dwordx4 v[124:127], v[114:115], off
	global_load_dwordx4 v[180:183], v[114:115], off offset:16
	v_mad_i64_i32 v[114:115], s[12:13], v162, s82, v[148:149]
	v_lshl_add_u64 v[114:115], v[114:115], 0, v[142:143]
	global_load_dwordx2 v[128:129], v[114:115], off offset:512
	global_load_dwordx2 v[192:193], v[114:115], off offset:544
	s_nop 0
	global_load_dwordx2 v[114:115], v[194:195], off offset:544
	v_mul_f32_e32 v134, v109, v109
	s_waitcnt vmcnt(6)
	v_pk_mul_f32 v[116:117], v[164:165], v[116:117]
	s_waitcnt vmcnt(5)
	v_pk_mul_f32 v[122:123], v[136:137], v[122:123]
	v_pk_mul_f32 v[120:121], v[138:139], v[120:121]
	s_waitcnt vmcnt(4)
	v_mov_b32_e32 v136, v125
	v_mov_b32_e32 v137, v127
	s_waitcnt vmcnt(3)
	v_mov_b32_e32 v138, v181
	v_mov_b32_e32 v139, v183
	v_pk_mul_f32 v[118:119], v[186:187], v[118:119]
	v_mov_b32_e32 v181, v182
	v_mov_b32_e32 v125, v126
	v_pk_mul_f32 v[126:127], v[120:121], v[136:137]
	v_pk_mul_f32 v[164:165], v[122:123], v[138:139]
	v_pk_mul_f32 v[136:137], v[116:117], v[136:137]
	v_pk_mul_f32 v[138:139], v[118:119], v[138:139]
	v_pk_fma_f32 v[118:119], v[118:119], v[180:181], v[164:165] neg_lo:[0,0,1] neg_hi:[0,0,1]
	v_pk_fma_f32 v[116:117], v[116:117], v[124:125], v[126:127] neg_lo:[0,0,1] neg_hi:[0,0,1]
	v_pk_fma_f32 v[122:123], v[122:123], v[180:181], v[138:139]
	v_pk_fma_f32 v[120:121], v[120:121], v[124:125], v[136:137]
	v_cvt_pk_bf16_f32 v116, v116, v117
	v_cvt_pk_bf16_f32 v117, v118, v119
	v_cvt_pk_bf16_f32 v118, v120, v121
	v_cvt_pk_bf16_f32 v119, v122, v123
	global_store_dwordx2 v[190:191], v[116:117], off offset:128 nt
	global_store_dwordx2 v[190:191], v[118:119], off offset:160 nt
	global_load_dwordx4 v[116:119], v[144:145], off
	v_pk_mul_f32 v[122:123], v[110:111], v[110:111]
	v_pk_mul_f32 v[120:121], v[112:113], v[112:113]
	v_mul_f32_e32 v122, v107, v107
	v_fmac_f32_e32 v123, v110, v110
	v_mul_f32_e32 v124, v103, v103
	v_pk_fma_f32 v[184:185], v[106:107], v[106:107], v[122:123] op_sel_hi:[1,1,0]
	v_pk_fma_f32 v[124:125], v[102:103], v[102:103], v[124:125] op_sel_hi:[1,1,0]
	v_add_f32_e32 v120, v120, v123
	v_pk_fma_f32 v[122:123], v[108:109], v[108:109], v[184:185]
	v_mul_f32_e32 v182, v105, v105
	v_pk_fma_f32 v[124:125], v[104:105], v[104:105], v[124:125]
	v_pk_add_f32 v[122:123], v[134:135], v[122:123] op_sel_hi:[0,1]
	v_pk_add_f32 v[124:125], v[182:183], v[124:125] op_sel_hi:[0,1]
	v_fmamk_f32 v123, v179, 0x3b800000, v174
	v_mov_b32_e32 v136, v99
	s_waitcnt vmcnt(5)
	v_and_b32_e32 v137, 0xffff0000, v128
	v_mul_f32_e32 v125, 0x4b800000, v123
	v_cmp_gt_f32_e32 vcc, s83, v123
	v_mov_b32_e32 v126, v98
	v_lshlrev_b32_e32 v127, 16, v128
	v_lshlrev_b32_e32 v139, 16, v129
	v_and_b32_e32 v165, 0xffff0000, v129
	s_waitcnt vmcnt(4)
	v_and_b32_e32 v129, 0xffff0000, v192
	v_lshlrev_b32_e32 v182, 16, v193
	v_pk_mul_f32 v[184:185], v[136:137], v[136:137]
	v_cndmask_b32_e32 v136, v123, v125, vcc
	v_mov_b32_e32 v180, v113
	v_lshlrev_b32_e32 v181, 16, v192
	v_and_b32_e32 v183, 0xffff0000, v193
	v_mul_f32_e32 v121, v129, v129
	v_mul_f32_e32 v128, v182, v182
	v_pk_fma_f32 v[184:185], v[126:127], v[126:127], v[184:185]
	v_rsq_f32_e32 v126, v136
	v_mov_b32_e32 v138, v100
	v_mul_f32_e32 v134, v183, v183
	v_pk_fma_f32 v[120:121], v[180:181], v[180:181], v[120:121]
	v_mov_b32_e32 v123, v128
	v_mov_b32_e32 v164, v101
	v_mov_b32_e32 v125, v134
	v_pk_fma_f32 v[184:185], v[138:139], v[138:139], v[184:185]
	v_pk_add_f32 v[120:121], v[120:121], v[122:123]
	v_pk_fma_f32 v[122:123], v[164:165], v[164:165], v[184:185]
	v_pk_add_f32 v[120:121], v[120:121], v[124:125]
	v_mov_b32_e32 v128, v181
	v_pk_add_f32 v[120:121], v[122:123], v[120:121]
	v_mul_f32_e32 v122, 0x45800000, v126
	v_cndmask_b32_e32 v124, v126, v122, vcc
	v_mul_f32_e32 v122, v124, v124
	v_fmac_f32_e32 v121, v120, v122
	ds_bpermute_b32 v120, v178, v121
	v_mov_b32_e32 v136, v127
	v_mov_b32_e32 v164, v139
	s_waitcnt lgkmcnt(0)
	v_add_f32_e32 v122, v121, v120
	ds_bpermute_b32 v123, v177, v122
	v_lshl_add_u64 v[120:121], v[162:163], 3, s[62:63]
	s_waitcnt lgkmcnt(0)
	v_add_f32_e32 v122, v122, v123
	v_fmamk_f32 v122, v122, 0x3c2aaaab, v174
	v_mul_f32_e32 v123, 0x4b800000, v122
	v_cmp_gt_f32_e32 vcc, s83, v122
	s_waitcnt vmcnt(0)
	v_pk_mov_b32 v[184:185], v[116:117], v[118:119] op_sel:[1,0]
	v_cndmask_b32_e32 v122, v122, v123, vcc
	v_rsq_f32_e32 v125, v122
	v_mad_u64_u32 v[122:123], s[12:13], v120, s69, v[146:147]
	v_mad_i32_i24 v123, v121, s69, v123
	v_lshl_add_u64 v[120:121], v[122:123], 0, v[142:143]
	v_mul_f32_e32 v122, 0x45800000, v125
	v_cndmask_b32_e32 v122, v125, v122, vcc
	v_mul_f32_e32 v124, v124, v122
	v_pk_mul_f32 v[110:111], v[110:111], v[124:125] op_sel_hi:[1,0]
	v_pk_mul_f32 v[112:113], v[112:113], v[124:125] op_sel_hi:[1,0]
	v_mov_b32_e32 v118, v185
	v_mov_b32_e32 v117, v184
	v_pk_mul_f32 v[112:113], v[118:119], v[112:113]
	v_pk_mul_f32 v[110:111], v[116:117], v[110:111]
	v_pk_mul_f32 v[106:107], v[106:107], v[124:125] op_sel_hi:[1,0]
	v_cvt_pk_bf16_f32 v110, v110, v111
	v_cvt_pk_bf16_f32 v111, v112, v113
	global_store_dwordx2 v[120:121], v[110:111], off nt
	global_load_dwordx4 v[110:113], v[144:145], off offset:64
	v_pk_mul_f32 v[108:109], v[108:109], v[124:125] op_sel_hi:[1,0]
	v_pk_mul_f32 v[102:103], v[102:103], v[124:125] op_sel_hi:[1,0]
	v_pk_mul_f32 v[104:105], v[104:105], v[124:125] op_sel_hi:[1,0]
	v_cmp_gt_i32_e32 vcc, s70, v162
	v_pk_mul_f32 v[98:99], v[98:99], v[124:125] op_sel_hi:[1,0]
	v_pk_mul_f32 v[100:101], v[100:101], v[124:125] op_sel_hi:[1,0]
	v_pk_mul_f32 v[124:125], v[128:129], v[122:123] op_sel_hi:[1,0]
	v_pk_mul_f32 v[118:119], v[136:137], v[122:123] op_sel_hi:[1,0]
	s_waitcnt vmcnt(0)
	v_pk_mov_b32 v[116:117], v[110:111], v[112:113] op_sel:[1,0]
	s_nop 0
	v_mov_b32_e32 v112, v117
	v_mov_b32_e32 v111, v116
	v_pk_mul_f32 v[108:109], v[112:113], v[108:109]
	v_pk_mul_f32 v[106:107], v[110:111], v[106:107]
	v_pk_mul_f32 v[116:117], v[164:165], v[122:123] op_sel_hi:[1,0]
	v_cvt_pk_bf16_f32 v106, v106, v107
	v_cvt_pk_bf16_f32 v107, v108, v109
	global_store_dwordx2 v[120:121], v[106:107], off offset:32 nt
	global_load_dwordx4 v[106:109], v[144:145], off offset:128
	v_pk_mul_f32 v[122:123], v[182:183], v[122:123] op_sel_hi:[1,0]
	s_waitcnt vmcnt(0)
	v_pk_mov_b32 v[110:111], v[106:107], v[108:109] op_sel:[1,0]
	s_nop 0
	v_mov_b32_e32 v108, v111
	v_mov_b32_e32 v107, v110
	v_pk_mul_f32 v[104:105], v[104:105], v[108:109]
	v_pk_mul_f32 v[102:103], v[102:103], v[106:107]
	v_cndmask_b32_e32 v106, v175, v176, vcc
	v_cvt_pk_bf16_f32 v102, v102, v103
	v_cvt_pk_bf16_f32 v103, v104, v105
	global_store_dwordx2 v[120:121], v[102:103], off offset:64 nt
	global_load_dwordx4 v[102:105], v[144:145], off offset:192
	v_and_b32_e32 v106, v106, v162
	v_lshlrev_b32_e32 v134, 4, v106
	v_lshl_add_u64 v[106:107], v[134:135], 0, v[140:141]
	v_lshl_add_u64 v[110:111], v[106:107], 3, s[44:45]
	s_waitcnt vmcnt(0)
	v_pk_mov_b32 v[106:107], v[102:103], v[104:105] op_sel:[1,0]
	s_nop 0
	v_mov_b32_e32 v104, v107
	v_mov_b32_e32 v103, v106
	v_pk_mul_f32 v[100:101], v[100:101], v[104:105]
	v_pk_mul_f32 v[98:99], v[98:99], v[102:103]
	s_nop 0
	v_cvt_pk_bf16_f32 v98, v98, v99
	v_cvt_pk_bf16_f32 v99, v100, v101
	global_store_dwordx2 v[120:121], v[98:99], off offset:96 nt
	global_load_dwordx4 v[98:101], v[144:145], off offset:256
	s_nop 0
	global_load_dwordx4 v[102:105], v[144:145], off offset:320
	global_load_dwordx4 v[106:109], v[110:111], off
	s_nop 0
	global_load_dwordx4 v[110:113], v[110:111], off offset:16
	s_waitcnt vmcnt(3)
	v_pk_mov_b32 v[126:127], v[98:99], v[100:101] op_sel:[1,0]
	s_waitcnt vmcnt(2)
	v_pk_mov_b32 v[128:129], v[102:103], v[104:105] op_sel:[1,0]
	s_waitcnt vmcnt(1)
	v_mov_b32_e32 v136, v107
	v_mov_b32_e32 v104, v129
	v_mov_b32_e32 v103, v128
	v_mov_b32_e32 v137, v109
	s_waitcnt vmcnt(0)
	v_mov_b32_e32 v138, v111
	v_mov_b32_e32 v139, v113
	v_mov_b32_e32 v99, v126
	v_mov_b32_e32 v100, v127
	v_pk_mul_f32 v[104:105], v[122:123], v[104:105]
	v_pk_mul_f32 v[102:103], v[124:125], v[102:103]
	v_mov_b32_e32 v111, v112
	v_mov_b32_e32 v107, v108
	v_pk_mul_f32 v[98:99], v[118:119], v[98:99]
	v_pk_mul_f32 v[100:101], v[116:117], v[100:101]
	v_pk_mul_f32 v[108:109], v[102:103], v[136:137]
	v_pk_mul_f32 v[112:113], v[104:105], v[138:139]
	v_pk_mul_f32 v[116:117], v[98:99], v[136:137]
	v_pk_mul_f32 v[118:119], v[100:101], v[138:139]
	v_pk_fma_f32 v[100:101], v[100:101], v[110:111], v[112:113] neg_lo:[0,0,1] neg_hi:[0,0,1]
	v_pk_fma_f32 v[98:99], v[98:99], v[106:107], v[108:109] neg_lo:[0,0,1] neg_hi:[0,0,1]
	v_pk_fma_f32 v[104:105], v[104:105], v[110:111], v[118:119]
	v_pk_fma_f32 v[102:103], v[102:103], v[106:107], v[116:117]
	v_cvt_pk_bf16_f32 v98, v98, v99
	v_cvt_pk_bf16_f32 v99, v100, v101
	v_cvt_pk_bf16_f32 v100, v102, v103
	v_cvt_pk_bf16_f32 v101, v104, v105
	global_store_dwordx2 v[120:121], v[98:99], off offset:128 nt
	global_store_dwordx2 v[120:121], v[100:101], off offset:160 nt
	global_load_dwordx4 v[98:101], v[144:145], off
	v_pk_mul_f32 v[104:105], v[94:95], v[94:95]
	v_pk_mul_f32 v[102:103], v[96:97], v[96:97]
	v_mul_f32_e32 v104, v91, v91
	v_fmac_f32_e32 v105, v94, v94
	v_mul_f32_e32 v106, v87, v87
	v_pk_fma_f32 v[124:125], v[90:91], v[90:91], v[104:105] op_sel_hi:[1,1,0]
	v_mul_f32_e32 v120, v93, v93
	v_pk_fma_f32 v[106:107], v[86:87], v[86:87], v[106:107] op_sel_hi:[1,1,0]
	v_add_f32_e32 v102, v102, v105
	v_pk_fma_f32 v[104:105], v[92:93], v[92:93], v[124:125]
	v_mul_f32_e32 v122, v89, v89
	v_pk_fma_f32 v[106:107], v[88:89], v[88:89], v[106:107]
	v_pk_add_f32 v[104:105], v[120:121], v[104:105] op_sel_hi:[0,1]
	v_pk_add_f32 v[106:107], v[122:123], v[106:107] op_sel_hi:[0,1]
	v_fmamk_f32 v105, v166, 0x3b800000, v174
	v_mov_b32_e32 v110, v83
	v_and_b32_e32 v111, 0xffff0000, v160
	v_mul_f32_e32 v107, 0x4b800000, v105
	v_cmp_gt_f32_e32 vcc, s83, v105
	v_mov_b32_e32 v108, v82
	v_lshlrev_b32_e32 v109, 16, v160
	v_lshlrev_b32_e32 v119, 16, v114
	v_and_b32_e32 v121, 0xffff0000, v114
	v_lshlrev_b32_e32 v114, 16, v115
	v_pk_mul_f32 v[122:123], v[110:111], v[110:111]
	v_cndmask_b32_e32 v110, v105, v107, vcc
	v_mov_b32_e32 v118, v97
	v_and_b32_e32 v115, 0xffff0000, v115
	v_mul_f32_e32 v103, v121, v121
	v_mul_f32_e32 v120, v114, v114
	v_pk_fma_f32 v[122:123], v[108:109], v[108:109], v[122:123]
	v_rsq_f32_e32 v108, v110
	v_mov_b32_e32 v112, v84
	v_lshlrev_b32_e32 v113, 16, v161
	v_mul_f32_e32 v124, v115, v115
	v_pk_fma_f32 v[102:103], v[118:119], v[118:119], v[102:103]
	v_mov_b32_e32 v105, v120
	v_mov_b32_e32 v116, v85
	v_and_b32_e32 v117, 0xffff0000, v161
	v_mov_b32_e32 v107, v124
	v_pk_fma_f32 v[122:123], v[112:113], v[112:113], v[122:123]
	v_pk_add_f32 v[102:103], v[102:103], v[104:105]
	v_pk_fma_f32 v[104:105], v[116:117], v[116:117], v[122:123]
	v_pk_add_f32 v[102:103], v[102:103], v[106:107]
	v_mov_b32_e32 v110, v109
	v_pk_add_f32 v[102:103], v[104:105], v[102:103]
	v_mul_f32_e32 v104, 0x45800000, v108
	v_cndmask_b32_e32 v106, v108, v104, vcc
	v_mul_f32_e32 v104, v106, v106
	v_fmac_f32_e32 v103, v102, v104
	ds_bpermute_b32 v102, v178, v103
	v_mov_b32_e32 v120, v119
	v_mov_b32_e32 v116, v113
	s_waitcnt lgkmcnt(0)
	v_add_f32_e32 v104, v103, v102
	ds_bpermute_b32 v105, v177, v104
	v_lshl_add_u64 v[102:103], v[158:159], 3, s[62:63]
	s_waitcnt lgkmcnt(0)
	v_add_f32_e32 v104, v104, v105
	v_fmamk_f32 v104, v104, 0x3c2aaaab, v174
	v_mul_f32_e32 v105, 0x4b800000, v104
	v_cmp_gt_f32_e32 vcc, s83, v104
	s_waitcnt vmcnt(0)
	v_pk_mov_b32 v[122:123], v[98:99], v[100:101] op_sel:[1,0]
	v_cndmask_b32_e32 v104, v104, v105, vcc
	v_rsq_f32_e32 v107, v104
	v_mad_u64_u32 v[104:105], s[12:13], v102, s69, v[146:147]
	v_mad_i32_i24 v105, v103, s69, v105
	v_lshl_add_u64 v[102:103], v[104:105], 0, v[142:143]
	v_mul_f32_e32 v104, 0x45800000, v107
	v_cndmask_b32_e32 v104, v107, v104, vcc
	v_mul_f32_e32 v106, v106, v104
	v_pk_mul_f32 v[94:95], v[94:95], v[106:107] op_sel_hi:[1,0]
	v_pk_mul_f32 v[96:97], v[96:97], v[106:107] op_sel_hi:[1,0]
	v_mov_b32_e32 v100, v123
	v_mov_b32_e32 v99, v122
	v_pk_mul_f32 v[96:97], v[100:101], v[96:97]
	v_pk_mul_f32 v[94:95], v[98:99], v[94:95]
	v_pk_mul_f32 v[90:91], v[90:91], v[106:107] op_sel_hi:[1,0]
	v_cvt_pk_bf16_f32 v94, v94, v95
	v_cvt_pk_bf16_f32 v95, v96, v97
	global_store_dwordx2 v[102:103], v[94:95], off nt
	global_load_dwordx4 v[94:97], v[144:145], off offset:64
	v_pk_mul_f32 v[92:93], v[92:93], v[106:107] op_sel_hi:[1,0]
	v_pk_mul_f32 v[86:87], v[86:87], v[106:107] op_sel_hi:[1,0]
	v_pk_mul_f32 v[88:89], v[88:89], v[106:107] op_sel_hi:[1,0]
	v_cmp_gt_i32_e32 vcc, s70, v158
	v_pk_mul_f32 v[82:83], v[82:83], v[106:107] op_sel_hi:[1,0]
	v_pk_mul_f32 v[84:85], v[84:85], v[106:107] op_sel_hi:[1,0]
	v_pk_mul_f32 v[100:101], v[110:111], v[104:105] op_sel_hi:[1,0]
	v_pk_mul_f32 v[106:107], v[120:121], v[104:105] op_sel_hi:[1,0]
	s_waitcnt vmcnt(0)
	v_pk_mov_b32 v[98:99], v[94:95], v[96:97] op_sel:[1,0]
	s_nop 0
	v_mov_b32_e32 v96, v99
	v_mov_b32_e32 v95, v98
	v_pk_mul_f32 v[92:93], v[96:97], v[92:93]
	v_pk_mul_f32 v[90:91], v[94:95], v[90:91]
	v_pk_mul_f32 v[98:99], v[116:117], v[104:105] op_sel_hi:[1,0]
	v_cvt_pk_bf16_f32 v90, v90, v91
	v_cvt_pk_bf16_f32 v91, v92, v93
	global_store_dwordx2 v[102:103], v[90:91], off offset:32 nt
	global_load_dwordx4 v[90:93], v[144:145], off offset:128
	v_pk_mul_f32 v[104:105], v[114:115], v[104:105] op_sel_hi:[1,0]
	s_waitcnt vmcnt(0)
	v_pk_mov_b32 v[94:95], v[90:91], v[92:93] op_sel:[1,0]
	s_nop 0
	v_mov_b32_e32 v92, v95
	v_mov_b32_e32 v91, v94
	v_pk_mul_f32 v[88:89], v[88:89], v[92:93]
	v_pk_mul_f32 v[86:87], v[86:87], v[90:91]
	v_cndmask_b32_e32 v90, v175, v176, vcc
	v_cvt_pk_bf16_f32 v86, v86, v87
	v_cvt_pk_bf16_f32 v87, v88, v89
	global_store_dwordx2 v[102:103], v[86:87], off offset:64 nt
	global_load_dwordx4 v[86:89], v[144:145], off offset:192
	v_and_b32_e32 v90, v90, v158
	v_lshlrev_b32_e32 v134, 4, v90
	v_lshl_add_u64 v[90:91], v[134:135], 0, v[140:141]
	v_lshl_add_u64 v[94:95], v[90:91], 3, s[44:45]
	s_waitcnt vmcnt(0)
	v_pk_mov_b32 v[90:91], v[86:87], v[88:89] op_sel:[1,0]
	s_nop 0
	v_mov_b32_e32 v88, v91
	v_mov_b32_e32 v87, v90
	v_pk_mul_f32 v[84:85], v[84:85], v[88:89]
	v_pk_mul_f32 v[82:83], v[82:83], v[86:87]
	s_nop 0
	v_cvt_pk_bf16_f32 v82, v82, v83
	v_cvt_pk_bf16_f32 v83, v84, v85
	global_store_dwordx2 v[102:103], v[82:83], off offset:96 nt
	global_load_dwordx4 v[82:85], v[144:145], off offset:256
	s_nop 0
	global_load_dwordx4 v[86:89], v[144:145], off offset:320
	global_load_dwordx4 v[90:93], v[94:95], off
	s_nop 0
	global_load_dwordx4 v[94:97], v[94:95], off offset:16
	s_waitcnt vmcnt(3)
	v_pk_mov_b32 v[108:109], v[82:83], v[84:85] op_sel:[1,0]
	s_waitcnt vmcnt(2)
	v_pk_mov_b32 v[110:111], v[86:87], v[88:89] op_sel:[1,0]
	s_waitcnt vmcnt(1)
	v_mov_b32_e32 v112, v91
	v_mov_b32_e32 v88, v111
	v_mov_b32_e32 v87, v110
	v_mov_b32_e32 v113, v93
	s_waitcnt vmcnt(0)
	v_mov_b32_e32 v114, v95
	v_mov_b32_e32 v115, v97
	v_mov_b32_e32 v83, v108
	v_mov_b32_e32 v84, v109
	v_pk_mul_f32 v[88:89], v[104:105], v[88:89]
	v_pk_mul_f32 v[86:87], v[106:107], v[86:87]
	v_mov_b32_e32 v95, v96
	v_mov_b32_e32 v91, v92
	v_pk_mul_f32 v[82:83], v[100:101], v[82:83]
	v_pk_mul_f32 v[84:85], v[98:99], v[84:85]
	v_pk_mul_f32 v[92:93], v[86:87], v[112:113]
	v_pk_mul_f32 v[96:97], v[88:89], v[114:115]
	v_pk_mul_f32 v[98:99], v[82:83], v[112:113]
	v_pk_mul_f32 v[100:101], v[84:85], v[114:115]
	v_pk_fma_f32 v[84:85], v[84:85], v[94:95], v[96:97] neg_lo:[0,0,1] neg_hi:[0,0,1]
	v_pk_fma_f32 v[82:83], v[82:83], v[90:91], v[92:93] neg_lo:[0,0,1] neg_hi:[0,0,1]
	v_pk_fma_f32 v[88:89], v[88:89], v[94:95], v[100:101]
	v_pk_fma_f32 v[86:87], v[86:87], v[90:91], v[98:99]
	v_cvt_pk_bf16_f32 v82, v82, v83
	v_cvt_pk_bf16_f32 v83, v84, v85
	v_cvt_pk_bf16_f32 v84, v86, v87
	v_cvt_pk_bf16_f32 v85, v88, v89
	global_store_dwordx2 v[102:103], v[82:83], off offset:128 nt
	global_store_dwordx2 v[102:103], v[84:85], off offset:160 nt
	global_load_dwordx4 v[82:85], v[144:145], off
	v_pk_mul_f32 v[88:89], v[78:79], v[78:79]
	v_pk_mul_f32 v[86:87], v[80:81], v[80:81]
	v_mul_f32_e32 v88, v75, v75
	v_fmac_f32_e32 v89, v78, v78
	v_mul_f32_e32 v90, v71, v71
	v_pk_fma_f32 v[106:107], v[74:75], v[74:75], v[88:89] op_sel_hi:[1,1,0]
	v_mul_f32_e32 v102, v77, v77
	v_pk_fma_f32 v[90:91], v[70:71], v[70:71], v[90:91] op_sel_hi:[1,1,0]
	v_add_f32_e32 v86, v86, v89
	v_pk_fma_f32 v[88:89], v[76:77], v[76:77], v[106:107]
	v_mul_f32_e32 v104, v73, v73
	v_pk_fma_f32 v[90:91], v[72:73], v[72:73], v[90:91]
	v_pk_add_f32 v[88:89], v[102:103], v[88:89] op_sel_hi:[0,1]
	v_pk_add_f32 v[90:91], v[104:105], v[90:91] op_sel_hi:[0,1]
	v_fmamk_f32 v89, v151, 0x3b800000, v174
	v_mov_b32_e32 v94, v67
	v_and_b32_e32 v95, 0xffff0000, v156
	v_mul_f32_e32 v91, 0x4b800000, v89
	v_cmp_gt_f32_e32 vcc, s83, v89
	v_mov_b32_e32 v92, v66
	v_lshlrev_b32_e32 v93, 16, v156
	v_and_b32_e32 v103, 0xffff0000, v154
	v_lshlrev_b32_e32 v104, 16, v155
	v_pk_mul_f32 v[106:107], v[94:95], v[94:95]
	v_cndmask_b32_e32 v94, v89, v91, vcc
	v_mov_b32_e32 v100, v81
	v_lshlrev_b32_e32 v101, 16, v154
	v_and_b32_e32 v105, 0xffff0000, v155
	v_mul_f32_e32 v87, v103, v103
	v_mul_f32_e32 v102, v104, v104
	v_pk_fma_f32 v[106:107], v[92:93], v[92:93], v[106:107]
	v_rsq_f32_e32 v92, v94
	v_mov_b32_e32 v96, v68
	v_lshlrev_b32_e32 v97, 16, v157
	v_mul_f32_e32 v108, v105, v105
	v_pk_fma_f32 v[86:87], v[100:101], v[100:101], v[86:87]
	v_mov_b32_e32 v89, v102
	v_mov_b32_e32 v98, v69
	v_and_b32_e32 v99, 0xffff0000, v157
	v_mov_b32_e32 v91, v108
	v_pk_fma_f32 v[106:107], v[96:97], v[96:97], v[106:107]
	v_pk_add_f32 v[86:87], v[86:87], v[88:89]
	v_pk_fma_f32 v[88:89], v[98:99], v[98:99], v[106:107]
	v_pk_add_f32 v[86:87], v[86:87], v[90:91]
	v_mov_b32_e32 v94, v93
	v_pk_add_f32 v[86:87], v[88:89], v[86:87]
	v_mul_f32_e32 v88, 0x45800000, v92
	v_cndmask_b32_e32 v90, v92, v88, vcc
	v_mul_f32_e32 v88, v90, v90
	v_fmac_f32_e32 v87, v86, v88
	ds_bpermute_b32 v86, v178, v87
	v_mov_b32_e32 v102, v101
	v_mov_b32_e32 v98, v97
	s_waitcnt lgkmcnt(0)
	v_add_f32_e32 v88, v87, v86
	ds_bpermute_b32 v89, v177, v88
	v_lshl_add_u64 v[86:87], v[152:153], 3, s[62:63]
	s_waitcnt lgkmcnt(0)
	v_add_f32_e32 v88, v88, v89
	v_fmamk_f32 v88, v88, 0x3c2aaaab, v174
	v_mul_f32_e32 v89, 0x4b800000, v88
	v_cmp_gt_f32_e32 vcc, s83, v88
	s_waitcnt vmcnt(0)
	v_pk_mov_b32 v[106:107], v[82:83], v[84:85] op_sel:[1,0]
	v_cndmask_b32_e32 v88, v88, v89, vcc
	v_rsq_f32_e32 v91, v88
	v_mad_u64_u32 v[88:89], s[12:13], v86, s69, v[146:147]
	v_mad_i32_i24 v89, v87, s69, v89
	v_lshl_add_u64 v[86:87], v[88:89], 0, v[142:143]
	v_mul_f32_e32 v88, 0x45800000, v91
	v_cndmask_b32_e32 v88, v91, v88, vcc
	v_mul_f32_e32 v90, v90, v88
	v_pk_mul_f32 v[78:79], v[78:79], v[90:91] op_sel_hi:[1,0]
	v_pk_mul_f32 v[80:81], v[80:81], v[90:91] op_sel_hi:[1,0]
	v_mov_b32_e32 v84, v107
	v_mov_b32_e32 v83, v106
	v_pk_mul_f32 v[80:81], v[84:85], v[80:81]
	v_pk_mul_f32 v[78:79], v[82:83], v[78:79]
	v_pk_mul_f32 v[74:75], v[74:75], v[90:91] op_sel_hi:[1,0]
	v_cvt_pk_bf16_f32 v78, v78, v79
	v_cvt_pk_bf16_f32 v79, v80, v81
	global_store_dwordx2 v[86:87], v[78:79], off nt
	global_load_dwordx4 v[78:81], v[144:145], off offset:64
	v_pk_mul_f32 v[76:77], v[76:77], v[90:91] op_sel_hi:[1,0]
	v_pk_mul_f32 v[70:71], v[70:71], v[90:91] op_sel_hi:[1,0]
	v_pk_mul_f32 v[72:73], v[72:73], v[90:91] op_sel_hi:[1,0]
	v_cmp_gt_i32_e32 vcc, s70, v152
	v_pk_mul_f32 v[66:67], v[66:67], v[90:91] op_sel_hi:[1,0]
	v_pk_mul_f32 v[68:69], v[68:69], v[90:91] op_sel_hi:[1,0]
	v_pk_mul_f32 v[92:93], v[98:99], v[88:89] op_sel_hi:[1,0]
	v_pk_mul_f32 v[94:95], v[94:95], v[88:89] op_sel_hi:[1,0]
	v_pk_mul_f32 v[96:97], v[102:103], v[88:89] op_sel_hi:[1,0]
	v_pk_mul_f32 v[88:89], v[104:105], v[88:89] op_sel_hi:[1,0]
	s_waitcnt vmcnt(0)
	v_pk_mov_b32 v[82:83], v[78:79], v[80:81] op_sel:[1,0]
	s_nop 0
	v_mov_b32_e32 v80, v83
	v_mov_b32_e32 v79, v82
	v_pk_mul_f32 v[76:77], v[80:81], v[76:77]
	v_pk_mul_f32 v[74:75], v[78:79], v[74:75]
	s_nop 0
	v_cvt_pk_bf16_f32 v74, v74, v75
	v_cvt_pk_bf16_f32 v75, v76, v77
	global_store_dwordx2 v[86:87], v[74:75], off offset:32 nt
	global_load_dwordx4 v[74:77], v[144:145], off offset:128
	s_waitcnt vmcnt(0)
	v_pk_mov_b32 v[78:79], v[74:75], v[76:77] op_sel:[1,0]
	s_nop 0
	v_mov_b32_e32 v76, v79
	v_mov_b32_e32 v75, v78
	v_pk_mul_f32 v[72:73], v[72:73], v[76:77]
	v_pk_mul_f32 v[70:71], v[70:71], v[74:75]
	v_cndmask_b32_e32 v74, v175, v176, vcc
	v_cvt_pk_bf16_f32 v70, v70, v71
	v_cvt_pk_bf16_f32 v71, v72, v73
	global_store_dwordx2 v[86:87], v[70:71], off offset:64 nt
	global_load_dwordx4 v[70:73], v[144:145], off offset:192
	v_and_b32_e32 v74, v74, v152
	v_lshlrev_b32_e32 v134, 4, v74
	v_lshl_add_u64 v[74:75], v[134:135], 0, v[140:141]
	v_lshl_add_u64 v[78:79], v[74:75], 3, s[44:45]
	s_waitcnt vmcnt(0)
	v_pk_mov_b32 v[74:75], v[70:71], v[72:73] op_sel:[1,0]
	s_nop 0
	v_mov_b32_e32 v72, v75
	v_mov_b32_e32 v71, v74
	v_pk_mul_f32 v[68:69], v[68:69], v[72:73]
	v_pk_mul_f32 v[66:67], v[66:67], v[70:71]
	s_nop 0
	v_cvt_pk_bf16_f32 v66, v66, v67
	v_cvt_pk_bf16_f32 v67, v68, v69
	global_store_dwordx2 v[86:87], v[66:67], off offset:96 nt
	global_load_dwordx4 v[66:69], v[144:145], off offset:256
	s_nop 0
	global_load_dwordx4 v[70:73], v[144:145], off offset:320
	global_load_dwordx4 v[74:77], v[78:79], off
	global_load_dwordx4 v[80:83], v[78:79], off offset:16
	v_add_u32_e32 v78, 0x80, v150
	v_ashrrev_i32_e32 v79, 31, v78
	v_mad_i64_i32 v[84:85], s[12:13], v78, s82, v[148:149]
	v_lshl_add_u64 v[90:91], v[78:79], 2, s[40:41]
	v_lshl_add_u64 v[84:85], v[84:85], 0, v[142:143]
	v_lshl_add_u64 v[108:109], v[78:79], 3, s[62:63]
	s_waitcnt vmcnt(3)
	v_pk_mov_b32 v[98:99], v[66:67], v[68:69] op_sel:[1,0]
	s_waitcnt vmcnt(2)
	v_pk_mov_b32 v[100:101], v[70:71], v[72:73] op_sel:[1,0]
	s_waitcnt vmcnt(1)
	v_mov_b32_e32 v102, v75
	v_mov_b32_e32 v72, v101
	v_mov_b32_e32 v71, v100
	v_mov_b32_e32 v103, v77
	s_waitcnt vmcnt(0)
	v_mov_b32_e32 v104, v81
	v_mov_b32_e32 v105, v83
	v_mov_b32_e32 v67, v98
	v_mov_b32_e32 v68, v99
	v_pk_mul_f32 v[72:73], v[88:89], v[72:73]
	v_pk_mul_f32 v[70:71], v[96:97], v[70:71]
	v_mov_b32_e32 v81, v82
	v_mov_b32_e32 v75, v76
	v_pk_mul_f32 v[66:67], v[94:95], v[66:67]
	v_pk_mul_f32 v[68:69], v[92:93], v[68:69]
	v_pk_mul_f32 v[76:77], v[70:71], v[102:103]
	v_pk_mul_f32 v[82:83], v[72:73], v[104:105]
	v_pk_mul_f32 v[88:89], v[66:67], v[102:103]
	v_pk_mul_f32 v[92:93], v[68:69], v[104:105]
	v_pk_fma_f32 v[68:69], v[68:69], v[80:81], v[82:83] neg_lo:[0,0,1] neg_hi:[0,0,1]
	v_pk_fma_f32 v[66:67], v[66:67], v[74:75], v[76:77] neg_lo:[0,0,1] neg_hi:[0,0,1]
	v_pk_fma_f32 v[72:73], v[72:73], v[80:81], v[92:93]
	v_pk_fma_f32 v[70:71], v[70:71], v[74:75], v[88:89]
	v_cvt_pk_bf16_f32 v66, v66, v67
	v_cvt_pk_bf16_f32 v67, v68, v69
	v_cvt_pk_bf16_f32 v68, v70, v71
	v_cvt_pk_bf16_f32 v69, v72, v73
	global_store_dwordx2 v[86:87], v[66:67], off offset:128 nt
	global_store_dwordx2 v[86:87], v[68:69], off offset:160 nt
	global_load_dword v81, v[90:91], off
	s_nop 0
	global_load_dwordx2 v[68:69], v[84:85], off offset:512
	global_load_dwordx2 v[70:71], v[84:85], off offset:544
	v_pk_mul_f32 v[72:73], v[62:63], v[62:63]
	global_load_dwordx4 v[82:85], v[144:145], off
	v_mul_f32_e32 v72, v59, v59
	v_mul_f32_e32 v74, v55, v55
	v_fmac_f32_e32 v73, v62, v62
	v_pk_fma_f32 v[76:77], v[58:59], v[58:59], v[72:73] op_sel_hi:[1,1,0]
	v_pk_fma_f32 v[74:75], v[54:55], v[54:55], v[74:75] op_sel_hi:[1,1,0]
	v_mul_f32_e32 v96, v57, v57
	v_pk_fma_f32 v[100:101], v[60:61], v[60:61], v[76:77]
	v_pk_fma_f32 v[74:75], v[56:57], v[56:57], v[74:75]
	v_add_u32_e32 v76, 0x90, v150
	v_pk_add_f32 v[74:75], v[96:97], v[74:75] op_sel_hi:[0,1]
	v_ashrrev_i32_e32 v77, 31, v76
	v_lshl_add_u64 v[102:103], v[76:77], 2, s[40:41]
	v_mov_b32_e32 v86, v51
	global_load_dword v112, v[102:103], off
	v_pk_mul_f32 v[66:67], v[64:65], v[64:65]
	v_mul_f32_e32 v94, v61, v61
	v_mov_b32_e32 v80, v50
	v_mov_b32_e32 v92, v65
	v_add_f32_e32 v98, v66, v73
	v_pk_add_f32 v[94:95], v[94:95], v[100:101] op_sel_hi:[0,1]
	v_mov_b32_e32 v88, v52
	v_mov_b32_e32 v90, v53
	v_add_u32_e32 v72, 0xa0, v150
	v_add_u32_e32 v66, 0xb0, v150
	v_ashrrev_i32_e32 v73, 31, v72
	v_mad_i64_i32 v[96:97], s[12:13], v72, s82, v[148:149]
	v_ashrrev_i32_e32 v67, 31, v66
	v_mad_i64_i32 v[100:101], s[12:13], v66, s82, v[148:149]
	v_lshl_add_u64 v[104:105], v[72:73], 2, s[40:41]
	v_lshl_add_u64 v[96:97], v[96:97], 0, v[142:143]
	v_lshl_add_u64 v[106:107], v[66:67], 2, s[40:41]
	v_lshl_add_u64 v[100:101], v[100:101], 0, v[142:143]
	s_waitcnt vmcnt(4)
	v_fmamk_f32 v75, v81, 0x3b800000, v174
	s_waitcnt vmcnt(3)
	v_and_b32_e32 v87, 0xffff0000, v68
	s_waitcnt vmcnt(2)
	v_lshlrev_b32_e32 v93, 16, v70
	v_and_b32_e32 v103, 0xffff0000, v70
	v_mul_f32_e32 v70, 0x4b800000, v75
	v_cmp_gt_f32_e32 vcc, s83, v75
	v_lshlrev_b32_e32 v81, 16, v68
	v_lshlrev_b32_e32 v89, 16, v69
	v_and_b32_e32 v91, 0xffff0000, v69
	v_pk_mul_f32 v[68:69], v[86:87], v[86:87]
	v_cndmask_b32_e32 v86, v75, v70, vcc
	v_lshlrev_b32_e32 v110, 16, v71
	v_and_b32_e32 v111, 0xffff0000, v71
	v_mul_f32_e32 v99, v103, v103
	v_rsq_f32_e32 v79, v86
	v_mul_f32_e32 v95, v110, v110
	v_mul_f32_e32 v102, v111, v111
	v_pk_fma_f32 v[68:69], v[80:81], v[80:81], v[68:69]
	v_pk_fma_f32 v[70:71], v[92:93], v[92:93], v[98:99]
	v_mov_b32_e32 v75, v102
	v_pk_fma_f32 v[68:69], v[88:89], v[88:89], v[68:69]
	v_pk_add_f32 v[70:71], v[70:71], v[94:95]
	v_pk_fma_f32 v[68:69], v[90:91], v[90:91], v[68:69]
	v_pk_add_f32 v[70:71], v[70:71], v[74:75]
	s_waitcnt vmcnt(1)
	v_pk_mov_b32 v[98:99], v[82:83], v[84:85] op_sel:[1,0]
	v_pk_add_f32 v[68:69], v[68:69], v[70:71]
	v_mul_f32_e32 v70, 0x45800000, v79
	v_cndmask_b32_e32 v86, v79, v70, vcc
	v_mul_f32_e32 v70, v86, v86
	v_fmac_f32_e32 v69, v68, v70
	ds_bpermute_b32 v68, v178, v69
	v_mad_u64_u32 v[70:71], s[12:13], v108, s69, v[146:147]
	v_mov_b32_e32 v84, v99
	v_mov_b32_e32 v83, v98
	s_waitcnt lgkmcnt(0)
	v_add_f32_e32 v88, v69, v68
	ds_bpermute_b32 v90, v177, v88
	v_mad_i32_i24 v71, v109, s69, v71
	v_lshl_add_u64 v[94:95], v[70:71], 0, v[142:143]
	global_load_dword v80, v[104:105], off
	global_load_dwordx2 v[74:75], v[96:97], off offset:512
	global_load_dword v79, v[106:107], off
	global_load_dwordx2 v[70:71], v[100:101], off offset:512
	global_load_dwordx2 v[68:69], v[100:101], off offset:544
	v_mov_b32_e32 v102, v93
	s_waitcnt lgkmcnt(0)
	v_add_f32_e32 v88, v88, v90
	v_fmamk_f32 v88, v88, 0x3c2aaaab, v174
	v_mul_f32_e32 v90, 0x4b800000, v88
	v_cmp_gt_f32_e32 vcc, s83, v88
	s_nop 1
	v_cndmask_b32_e32 v88, v88, v90, vcc
	v_rsq_f32_e32 v88, v88
	s_nop 0
	v_mul_f32_e32 v90, 0x45800000, v88
	v_cndmask_b32_e32 v88, v88, v90, vcc
	v_mul_f32_e32 v86, v86, v88
	v_pk_mul_f32 v[62:63], v[62:63], v[86:87] op_sel_hi:[1,0]
	v_pk_mul_f32 v[64:65], v[64:65], v[86:87] op_sel_hi:[1,0]
	v_pk_mul_f32 v[62:63], v[82:83], v[62:63]
	v_pk_mul_f32 v[64:65], v[84:85], v[64:65]
	v_cvt_pk_bf16_f32 v62, v62, v63
	v_cvt_pk_bf16_f32 v63, v64, v65
	global_store_dwordx2 v[94:95], v[62:63], off nt
	global_load_dwordx4 v[62:65], v[144:145], off offset:64
	v_pk_mul_f32 v[58:59], v[58:59], v[86:87] op_sel_hi:[1,0]
	v_pk_mul_f32 v[60:61], v[60:61], v[86:87] op_sel_hi:[1,0]
	v_pk_mul_f32 v[54:55], v[54:55], v[86:87] op_sel_hi:[1,0]
	v_pk_mul_f32 v[56:57], v[56:57], v[86:87] op_sel_hi:[1,0]
	v_cmp_gt_i32_e32 vcc, s70, v78
	v_pk_mul_f32 v[50:51], v[50:51], v[86:87] op_sel_hi:[1,0]
	v_pk_mul_f32 v[52:53], v[52:53], v[86:87] op_sel_hi:[1,0]
	v_mov_b32_e32 v86, v81
	v_mov_b32_e32 v90, v89
	v_pk_mul_f32 v[90:91], v[90:91], v[88:89] op_sel_hi:[1,0]
	v_pk_mul_f32 v[86:87], v[86:87], v[88:89] op_sel_hi:[1,0]
	v_pk_mul_f32 v[92:93], v[102:103], v[88:89] op_sel_hi:[1,0]
	v_pk_mul_f32 v[88:89], v[110:111], v[88:89] op_sel_hi:[1,0]
	s_waitcnt vmcnt(0)
	v_pk_mov_b32 v[82:83], v[62:63], v[64:65] op_sel:[1,0]
	s_nop 0
	v_mov_b32_e32 v64, v83
	v_mov_b32_e32 v63, v82
	v_pk_mul_f32 v[60:61], v[64:65], v[60:61]
	v_pk_mul_f32 v[58:59], v[62:63], v[58:59]
	s_nop 0
	v_cvt_pk_bf16_f32 v58, v58, v59
	v_cvt_pk_bf16_f32 v59, v60, v61
	global_store_dwordx2 v[94:95], v[58:59], off offset:32 nt
	global_load_dwordx4 v[58:61], v[144:145], off offset:128
	s_waitcnt vmcnt(0)
	v_pk_mov_b32 v[62:63], v[58:59], v[60:61] op_sel:[1,0]
	s_nop 0
	v_mov_b32_e32 v60, v63
	v_mov_b32_e32 v59, v62
	v_pk_mul_f32 v[56:57], v[56:57], v[60:61]
	v_pk_mul_f32 v[54:55], v[54:55], v[58:59]
	v_cndmask_b32_e32 v58, v175, v176, vcc
	v_cvt_pk_bf16_f32 v54, v54, v55
	v_cvt_pk_bf16_f32 v55, v56, v57
	global_store_dwordx2 v[94:95], v[54:55], off offset:64 nt
	global_load_dwordx4 v[54:57], v[144:145], off offset:192
	v_and_b32_e32 v58, v58, v78
	v_lshlrev_b32_e32 v134, 4, v58
	v_lshl_add_u64 v[58:59], v[134:135], 0, v[140:141]
	v_lshl_add_u64 v[64:65], v[58:59], 3, s[44:45]
	v_mul_f32_e32 v78, v45, v45
	s_waitcnt vmcnt(0)
	v_pk_mov_b32 v[58:59], v[54:55], v[56:57] op_sel:[1,0]
	s_nop 0
	v_mov_b32_e32 v56, v59
	v_mov_b32_e32 v55, v58
	v_pk_mul_f32 v[52:53], v[52:53], v[56:57]
	v_pk_mul_f32 v[50:51], v[50:51], v[54:55]
	s_nop 0
	v_cvt_pk_bf16_f32 v50, v50, v51
	v_cvt_pk_bf16_f32 v51, v52, v53
	global_store_dwordx2 v[94:95], v[50:51], off offset:96 nt
	global_load_dwordx4 v[52:55], v[144:145], off offset:256
	global_load_dwordx4 v[56:59], v[144:145], off offset:320
	global_load_dwordx4 v[60:63], v[64:65], off
	global_load_dwordx4 v[82:85], v[64:65], off offset:16
	v_mad_i64_i32 v[50:51], s[12:13], v76, s82, v[148:149]
	v_lshl_add_u64 v[50:51], v[50:51], 0, v[142:143]
	global_load_dwordx2 v[64:65], v[50:51], off offset:512
	global_load_dwordx2 v[98:99], v[50:51], off offset:544
	s_nop 0
	global_load_dwordx2 v[50:51], v[96:97], off offset:544
	s_waitcnt vmcnt(6)
	v_pk_mov_b32 v[96:97], v[52:53], v[54:55] op_sel:[1,0]
	s_waitcnt vmcnt(5)
	v_pk_mov_b32 v[100:101], v[56:57], v[58:59] op_sel:[1,0]
	s_waitcnt vmcnt(4)
	v_mov_b32_e32 v102, v61
	v_mov_b32_e32 v58, v101
	v_mov_b32_e32 v57, v100
	v_mov_b32_e32 v103, v63
	s_waitcnt vmcnt(3)
	v_mov_b32_e32 v104, v83
	v_mov_b32_e32 v105, v85
	v_mov_b32_e32 v53, v96
	v_mov_b32_e32 v54, v97
	v_pk_mul_f32 v[58:59], v[88:89], v[58:59]
	v_pk_mul_f32 v[56:57], v[92:93], v[56:57]
	v_mov_b32_e32 v83, v84
	v_mov_b32_e32 v61, v62
	v_pk_mul_f32 v[52:53], v[86:87], v[52:53]
	v_pk_mul_f32 v[54:55], v[90:91], v[54:55]
	v_pk_mul_f32 v[62:63], v[56:57], v[102:103]
	v_pk_mul_f32 v[84:85], v[58:59], v[104:105]
	v_pk_mul_f32 v[86:87], v[52:53], v[102:103]
	v_pk_mul_f32 v[88:89], v[54:55], v[104:105]
	v_pk_fma_f32 v[54:55], v[54:55], v[82:83], v[84:85] neg_lo:[0,0,1] neg_hi:[0,0,1]
	v_pk_fma_f32 v[52:53], v[52:53], v[60:61], v[62:63] neg_lo:[0,0,1] neg_hi:[0,0,1]
	v_pk_fma_f32 v[58:59], v[58:59], v[82:83], v[88:89]
	v_pk_fma_f32 v[56:57], v[56:57], v[60:61], v[86:87]
	v_cvt_pk_bf16_f32 v52, v52, v53
	v_cvt_pk_bf16_f32 v53, v54, v55
	v_cvt_pk_bf16_f32 v54, v56, v57
	v_cvt_pk_bf16_f32 v55, v58, v59
	global_store_dwordx2 v[94:95], v[52:53], off offset:128 nt
	global_store_dwordx2 v[94:95], v[54:55], off offset:160 nt
	global_load_dwordx4 v[52:55], v[144:145], off
	v_pk_mul_f32 v[58:59], v[46:47], v[46:47]
	v_pk_mul_f32 v[56:57], v[48:49], v[48:49]
	v_mul_f32_e32 v58, v43, v43
	v_fmac_f32_e32 v59, v46, v46
	v_mul_f32_e32 v60, v39, v39
	v_pk_fma_f32 v[92:93], v[42:43], v[42:43], v[58:59] op_sel_hi:[1,1,0]
	v_pk_fma_f32 v[60:61], v[38:39], v[38:39], v[60:61] op_sel_hi:[1,1,0]
	v_add_f32_e32 v56, v56, v59
	v_pk_fma_f32 v[58:59], v[44:45], v[44:45], v[92:93]
	v_mul_f32_e32 v90, v41, v41
	v_pk_fma_f32 v[60:61], v[40:41], v[40:41], v[60:61]
	v_pk_add_f32 v[58:59], v[78:79], v[58:59] op_sel_hi:[0,1]
	v_pk_add_f32 v[60:61], v[90:91], v[60:61] op_sel_hi:[0,1]
	v_fmamk_f32 v59, v112, 0x3b800000, v174
	v_mov_b32_e32 v82, v35
	s_waitcnt vmcnt(5)
	v_and_b32_e32 v83, 0xffff0000, v64
	v_mul_f32_e32 v61, 0x4b800000, v59
	v_cmp_gt_f32_e32 vcc, s83, v59
	v_mov_b32_e32 v62, v34
	v_lshlrev_b32_e32 v63, 16, v64
	v_lshlrev_b32_e32 v85, 16, v65
	v_and_b32_e32 v87, 0xffff0000, v65
	s_waitcnt vmcnt(4)
	v_and_b32_e32 v65, 0xffff0000, v98
	v_lshlrev_b32_e32 v90, 16, v99
	v_pk_mul_f32 v[92:93], v[82:83], v[82:83]
	v_cndmask_b32_e32 v81, v59, v61, vcc
	v_mov_b32_e32 v88, v49
	v_lshlrev_b32_e32 v89, 16, v98
	v_and_b32_e32 v91, 0xffff0000, v99
	v_mul_f32_e32 v57, v65, v65
	v_mul_f32_e32 v64, v90, v90
	v_pk_fma_f32 v[92:93], v[62:63], v[62:63], v[92:93]
	v_rsq_f32_e32 v62, v81
	v_mov_b32_e32 v84, v36
	v_mul_f32_e32 v78, v91, v91
	v_pk_fma_f32 v[56:57], v[88:89], v[88:89], v[56:57]
	v_mov_b32_e32 v59, v64
	v_mov_b32_e32 v86, v37
	v_mov_b32_e32 v61, v78
	v_pk_fma_f32 v[92:93], v[84:85], v[84:85], v[92:93]
	v_pk_add_f32 v[56:57], v[56:57], v[58:59]
	v_pk_fma_f32 v[58:59], v[86:87], v[86:87], v[92:93]
	v_pk_add_f32 v[56:57], v[56:57], v[60:61]
	v_mov_b32_e32 v64, v89
	v_pk_add_f32 v[56:57], v[58:59], v[56:57]
	v_mul_f32_e32 v58, 0x45800000, v62
	v_cndmask_b32_e32 v60, v62, v58, vcc
	v_mul_f32_e32 v58, v60, v60
	v_fmac_f32_e32 v57, v56, v58
	ds_bpermute_b32 v56, v178, v57
	v_mov_b32_e32 v82, v63
	v_mov_b32_e32 v86, v85
	s_waitcnt lgkmcnt(0)
	v_add_f32_e32 v58, v57, v56
	ds_bpermute_b32 v59, v177, v58
	v_lshl_add_u64 v[56:57], v[76:77], 3, s[62:63]
	s_waitcnt lgkmcnt(0)
	v_add_f32_e32 v58, v58, v59
	v_fmamk_f32 v58, v58, 0x3c2aaaab, v174
	v_mul_f32_e32 v59, 0x4b800000, v58
	v_cmp_gt_f32_e32 vcc, s83, v58
	s_waitcnt vmcnt(0)
	v_pk_mov_b32 v[92:93], v[52:53], v[54:55] op_sel:[1,0]
	v_cndmask_b32_e32 v58, v58, v59, vcc
	v_rsq_f32_e32 v61, v58
	v_mad_u64_u32 v[58:59], s[12:13], v56, s69, v[146:147]
	v_mad_i32_i24 v59, v57, s69, v59
	v_lshl_add_u64 v[56:57], v[58:59], 0, v[142:143]
	v_mul_f32_e32 v58, 0x45800000, v61
	v_cndmask_b32_e32 v58, v61, v58, vcc
	v_mul_f32_e32 v60, v60, v58
	v_pk_mul_f32 v[46:47], v[46:47], v[60:61] op_sel_hi:[1,0]
	v_pk_mul_f32 v[48:49], v[48:49], v[60:61] op_sel_hi:[1,0]
	v_mov_b32_e32 v54, v93
	v_mov_b32_e32 v53, v92
	v_pk_mul_f32 v[48:49], v[54:55], v[48:49]
	v_pk_mul_f32 v[46:47], v[52:53], v[46:47]
	v_pk_mul_f32 v[42:43], v[42:43], v[60:61] op_sel_hi:[1,0]
	v_cvt_pk_bf16_f32 v46, v46, v47
	v_cvt_pk_bf16_f32 v47, v48, v49
	global_store_dwordx2 v[56:57], v[46:47], off nt
	global_load_dwordx4 v[46:49], v[144:145], off offset:64
	v_pk_mul_f32 v[44:45], v[44:45], v[60:61] op_sel_hi:[1,0]
	v_pk_mul_f32 v[38:39], v[38:39], v[60:61] op_sel_hi:[1,0]
	v_pk_mul_f32 v[40:41], v[40:41], v[60:61] op_sel_hi:[1,0]
	v_cmp_gt_i32_e32 vcc, s70, v76
	v_pk_mul_f32 v[34:35], v[34:35], v[60:61] op_sel_hi:[1,0]
	v_pk_mul_f32 v[36:37], v[36:37], v[60:61] op_sel_hi:[1,0]
	v_pk_mul_f32 v[60:61], v[64:65], v[58:59] op_sel_hi:[1,0]
	v_pk_mul_f32 v[54:55], v[82:83], v[58:59] op_sel_hi:[1,0]
	s_waitcnt vmcnt(0)
	v_pk_mov_b32 v[52:53], v[46:47], v[48:49] op_sel:[1,0]
	s_nop 0
	v_mov_b32_e32 v48, v53
	v_mov_b32_e32 v47, v52
	v_pk_mul_f32 v[44:45], v[48:49], v[44:45]
	v_pk_mul_f32 v[42:43], v[46:47], v[42:43]
	v_pk_mul_f32 v[52:53], v[86:87], v[58:59] op_sel_hi:[1,0]
	v_cvt_pk_bf16_f32 v42, v42, v43
	v_cvt_pk_bf16_f32 v43, v44, v45
	global_store_dwordx2 v[56:57], v[42:43], off offset:32 nt
	global_load_dwordx4 v[42:45], v[144:145], off offset:128
	v_pk_mul_f32 v[58:59], v[90:91], v[58:59] op_sel_hi:[1,0]
	s_waitcnt vmcnt(0)
	v_pk_mov_b32 v[46:47], v[42:43], v[44:45] op_sel:[1,0]
	s_nop 0
	v_mov_b32_e32 v44, v47
	v_mov_b32_e32 v43, v46
	v_pk_mul_f32 v[40:41], v[40:41], v[44:45]
	v_pk_mul_f32 v[38:39], v[38:39], v[42:43]
	v_cndmask_b32_e32 v42, v175, v176, vcc
	v_cvt_pk_bf16_f32 v38, v38, v39
	v_cvt_pk_bf16_f32 v39, v40, v41
	global_store_dwordx2 v[56:57], v[38:39], off offset:64 nt
	global_load_dwordx4 v[38:41], v[144:145], off offset:192
	v_and_b32_e32 v42, v42, v76
	v_lshlrev_b32_e32 v134, 4, v42
	v_lshl_add_u64 v[42:43], v[134:135], 0, v[140:141]
	v_lshl_add_u64 v[46:47], v[42:43], 3, s[44:45]
	s_waitcnt vmcnt(0)
	v_pk_mov_b32 v[42:43], v[38:39], v[40:41] op_sel:[1,0]
	s_nop 0
	v_mov_b32_e32 v40, v43
	v_mov_b32_e32 v39, v42
	v_pk_mul_f32 v[36:37], v[36:37], v[40:41]
	v_pk_mul_f32 v[34:35], v[34:35], v[38:39]
	s_nop 0
	v_cvt_pk_bf16_f32 v34, v34, v35
	v_cvt_pk_bf16_f32 v35, v36, v37
	global_store_dwordx2 v[56:57], v[34:35], off offset:96 nt
	global_load_dwordx4 v[34:37], v[144:145], off offset:256
	s_nop 0
	global_load_dwordx4 v[38:41], v[144:145], off offset:320
	global_load_dwordx4 v[42:45], v[46:47], off
	s_nop 0
	global_load_dwordx4 v[46:49], v[46:47], off offset:16
	s_waitcnt vmcnt(3)
	v_pk_mov_b32 v[62:63], v[34:35], v[36:37] op_sel:[1,0]
	s_waitcnt vmcnt(2)
	v_pk_mov_b32 v[64:65], v[38:39], v[40:41] op_sel:[1,0]
	s_waitcnt vmcnt(1)
	v_mov_b32_e32 v76, v43
	v_mov_b32_e32 v40, v65
	v_mov_b32_e32 v39, v64
	v_mov_b32_e32 v77, v45
	s_waitcnt vmcnt(0)
	v_mov_b32_e32 v82, v47
	v_mov_b32_e32 v83, v49
	v_mov_b32_e32 v35, v62
	v_mov_b32_e32 v36, v63
	v_pk_mul_f32 v[40:41], v[58:59], v[40:41]
	v_pk_mul_f32 v[38:39], v[60:61], v[38:39]
	v_mov_b32_e32 v47, v48
	v_mov_b32_e32 v43, v44
	v_pk_mul_f32 v[34:35], v[54:55], v[34:35]
	v_pk_mul_f32 v[36:37], v[52:53], v[36:37]
	v_pk_mul_f32 v[44:45], v[38:39], v[76:77]
	v_pk_mul_f32 v[48:49], v[40:41], v[82:83]
	v_pk_mul_f32 v[52:53], v[34:35], v[76:77]
	v_pk_mul_f32 v[54:55], v[36:37], v[82:83]
	v_pk_fma_f32 v[36:37], v[36:37], v[46:47], v[48:49] neg_lo:[0,0,1] neg_hi:[0,0,1]
	v_pk_fma_f32 v[34:35], v[34:35], v[42:43], v[44:45] neg_lo:[0,0,1] neg_hi:[0,0,1]
	v_pk_fma_f32 v[40:41], v[40:41], v[46:47], v[54:55]
	v_pk_fma_f32 v[38:39], v[38:39], v[42:43], v[52:53]
	v_cvt_pk_bf16_f32 v34, v34, v35
	v_cvt_pk_bf16_f32 v35, v36, v37
	v_cvt_pk_bf16_f32 v36, v38, v39
	v_cvt_pk_bf16_f32 v37, v40, v41
	global_store_dwordx2 v[56:57], v[34:35], off offset:128 nt
	global_store_dwordx2 v[56:57], v[36:37], off offset:160 nt
	global_load_dwordx4 v[34:37], v[144:145], off
	v_pk_mul_f32 v[40:41], v[30:31], v[30:31]
	v_pk_mul_f32 v[38:39], v[32:33], v[32:33]
	v_mul_f32_e32 v40, v27, v27
	v_fmac_f32_e32 v41, v30, v30
	v_mul_f32_e32 v42, v23, v23
	v_pk_fma_f32 v[60:61], v[26:27], v[26:27], v[40:41] op_sel_hi:[1,1,0]
	v_mul_f32_e32 v56, v29, v29
	v_pk_fma_f32 v[42:43], v[22:23], v[22:23], v[42:43] op_sel_hi:[1,1,0]
	v_add_f32_e32 v38, v38, v41
	v_pk_fma_f32 v[40:41], v[28:29], v[28:29], v[60:61]
	v_mul_f32_e32 v58, v25, v25
	v_pk_fma_f32 v[42:43], v[24:25], v[24:25], v[42:43]
	v_pk_add_f32 v[40:41], v[56:57], v[40:41] op_sel_hi:[0,1]
	v_pk_add_f32 v[42:43], v[58:59], v[42:43] op_sel_hi:[0,1]
	v_fmamk_f32 v41, v80, 0x3b800000, v174
	v_mov_b32_e32 v46, v19
	v_and_b32_e32 v47, 0xffff0000, v74
	v_mul_f32_e32 v43, 0x4b800000, v41
	v_cmp_gt_f32_e32 vcc, s83, v41
	v_mov_b32_e32 v44, v18
	v_lshlrev_b32_e32 v45, 16, v74
	v_lshlrev_b32_e32 v55, 16, v50
	v_and_b32_e32 v57, 0xffff0000, v50
	v_lshlrev_b32_e32 v50, 16, v51
	v_pk_mul_f32 v[58:59], v[46:47], v[46:47]
	v_cndmask_b32_e32 v46, v41, v43, vcc
	v_mov_b32_e32 v54, v33
	v_and_b32_e32 v51, 0xffff0000, v51
	v_mul_f32_e32 v39, v57, v57
	v_mul_f32_e32 v56, v50, v50
	v_pk_fma_f32 v[58:59], v[44:45], v[44:45], v[58:59]
	v_rsq_f32_e32 v44, v46
	v_mov_b32_e32 v48, v20
	v_lshlrev_b32_e32 v49, 16, v75
	v_mul_f32_e32 v60, v51, v51
	v_pk_fma_f32 v[38:39], v[54:55], v[54:55], v[38:39]
	v_mov_b32_e32 v41, v56
	v_mov_b32_e32 v52, v21
	v_and_b32_e32 v53, 0xffff0000, v75
	v_mov_b32_e32 v43, v60
	v_pk_fma_f32 v[58:59], v[48:49], v[48:49], v[58:59]
	v_pk_add_f32 v[38:39], v[38:39], v[40:41]
	v_pk_fma_f32 v[40:41], v[52:53], v[52:53], v[58:59]
	v_pk_add_f32 v[38:39], v[38:39], v[42:43]
	v_mov_b32_e32 v46, v45
	v_pk_add_f32 v[38:39], v[40:41], v[38:39]
	v_mul_f32_e32 v40, 0x45800000, v44
	v_cndmask_b32_e32 v42, v44, v40, vcc
	v_mul_f32_e32 v40, v42, v42
	v_fmac_f32_e32 v39, v38, v40
	ds_bpermute_b32 v38, v178, v39
	v_mov_b32_e32 v56, v55
	v_mov_b32_e32 v52, v49
	s_waitcnt lgkmcnt(0)
	v_add_f32_e32 v40, v39, v38
	ds_bpermute_b32 v41, v177, v40
	v_lshl_add_u64 v[38:39], v[72:73], 3, s[62:63]
	s_waitcnt lgkmcnt(0)
	v_add_f32_e32 v40, v40, v41
	v_fmamk_f32 v40, v40, 0x3c2aaaab, v174
	v_mul_f32_e32 v41, 0x4b800000, v40
	v_cmp_gt_f32_e32 vcc, s83, v40
	s_waitcnt vmcnt(0)
	v_pk_mov_b32 v[58:59], v[34:35], v[36:37] op_sel:[1,0]
	v_cndmask_b32_e32 v40, v40, v41, vcc
	v_rsq_f32_e32 v43, v40
	v_mad_u64_u32 v[40:41], s[12:13], v38, s69, v[146:147]
	v_mad_i32_i24 v41, v39, s69, v41
	v_lshl_add_u64 v[38:39], v[40:41], 0, v[142:143]
	v_mul_f32_e32 v40, 0x45800000, v43
	v_cndmask_b32_e32 v40, v43, v40, vcc
	v_mul_f32_e32 v42, v42, v40
	v_pk_mul_f32 v[30:31], v[30:31], v[42:43] op_sel_hi:[1,0]
	v_pk_mul_f32 v[32:33], v[32:33], v[42:43] op_sel_hi:[1,0]
	v_mov_b32_e32 v36, v59
	v_mov_b32_e32 v35, v58
	v_pk_mul_f32 v[32:33], v[36:37], v[32:33]
	v_pk_mul_f32 v[30:31], v[34:35], v[30:31]
	v_pk_mul_f32 v[26:27], v[26:27], v[42:43] op_sel_hi:[1,0]
	v_cvt_pk_bf16_f32 v30, v30, v31
	v_cvt_pk_bf16_f32 v31, v32, v33
	global_store_dwordx2 v[38:39], v[30:31], off nt
	global_load_dwordx4 v[30:33], v[144:145], off offset:64
	v_pk_mul_f32 v[28:29], v[28:29], v[42:43] op_sel_hi:[1,0]
	v_pk_mul_f32 v[22:23], v[22:23], v[42:43] op_sel_hi:[1,0]
	v_pk_mul_f32 v[24:25], v[24:25], v[42:43] op_sel_hi:[1,0]
	v_cmp_gt_i32_e32 vcc, s70, v72
	v_pk_mul_f32 v[18:19], v[18:19], v[42:43] op_sel_hi:[1,0]
	v_pk_mul_f32 v[20:21], v[20:21], v[42:43] op_sel_hi:[1,0]
	v_pk_mul_f32 v[36:37], v[46:47], v[40:41] op_sel_hi:[1,0]
	v_pk_mul_f32 v[42:43], v[56:57], v[40:41] op_sel_hi:[1,0]
	s_waitcnt vmcnt(0)
	v_pk_mov_b32 v[34:35], v[30:31], v[32:33] op_sel:[1,0]
	s_nop 0
	v_mov_b32_e32 v32, v35
	v_mov_b32_e32 v31, v34
	v_pk_mul_f32 v[28:29], v[32:33], v[28:29]
	v_pk_mul_f32 v[26:27], v[30:31], v[26:27]
	v_pk_mul_f32 v[34:35], v[52:53], v[40:41] op_sel_hi:[1,0]
	v_cvt_pk_bf16_f32 v26, v26, v27
	v_cvt_pk_bf16_f32 v27, v28, v29
	global_store_dwordx2 v[38:39], v[26:27], off offset:32 nt
	global_load_dwordx4 v[26:29], v[144:145], off offset:128
	v_pk_mul_f32 v[40:41], v[50:51], v[40:41] op_sel_hi:[1,0]
	s_waitcnt vmcnt(0)
	v_pk_mov_b32 v[30:31], v[26:27], v[28:29] op_sel:[1,0]
	s_nop 0
	v_mov_b32_e32 v28, v31
	v_mov_b32_e32 v27, v30
	v_pk_mul_f32 v[24:25], v[24:25], v[28:29]
	v_pk_mul_f32 v[22:23], v[22:23], v[26:27]
	v_cndmask_b32_e32 v26, v175, v176, vcc
	v_cvt_pk_bf16_f32 v22, v22, v23
	v_cvt_pk_bf16_f32 v23, v24, v25
	global_store_dwordx2 v[38:39], v[22:23], off offset:64 nt
	global_load_dwordx4 v[22:25], v[144:145], off offset:192
	v_and_b32_e32 v26, v26, v72
	v_lshlrev_b32_e32 v134, 4, v26
	v_lshl_add_u64 v[26:27], v[134:135], 0, v[140:141]
	v_lshl_add_u64 v[30:31], v[26:27], 3, s[44:45]
	s_waitcnt vmcnt(0)
	v_pk_mov_b32 v[26:27], v[22:23], v[24:25] op_sel:[1,0]
	s_nop 0
	v_mov_b32_e32 v24, v27
	v_mov_b32_e32 v23, v26
	v_pk_mul_f32 v[20:21], v[20:21], v[24:25]
	v_pk_mul_f32 v[18:19], v[18:19], v[22:23]
	s_nop 0
	v_cvt_pk_bf16_f32 v18, v18, v19
	v_cvt_pk_bf16_f32 v19, v20, v21
	global_store_dwordx2 v[38:39], v[18:19], off offset:96 nt
	global_load_dwordx4 v[18:21], v[144:145], off offset:256
	s_nop 0
	global_load_dwordx4 v[22:25], v[144:145], off offset:320
	global_load_dwordx4 v[26:29], v[30:31], off
	s_nop 0
	global_load_dwordx4 v[30:33], v[30:31], off offset:16
	s_waitcnt vmcnt(3)
	v_pk_mov_b32 v[44:45], v[18:19], v[20:21] op_sel:[1,0]
	s_waitcnt vmcnt(2)
	v_pk_mov_b32 v[46:47], v[22:23], v[24:25] op_sel:[1,0]
	s_waitcnt vmcnt(1)
	v_mov_b32_e32 v48, v27
	v_mov_b32_e32 v24, v47
	v_mov_b32_e32 v23, v46
	v_mov_b32_e32 v49, v29
	s_waitcnt vmcnt(0)
	v_mov_b32_e32 v50, v31
	v_mov_b32_e32 v51, v33
	v_mov_b32_e32 v19, v44
	v_mov_b32_e32 v20, v45
	v_pk_mul_f32 v[24:25], v[40:41], v[24:25]
	v_pk_mul_f32 v[22:23], v[42:43], v[22:23]
	v_mov_b32_e32 v31, v32
	v_mov_b32_e32 v27, v28
	v_pk_mul_f32 v[18:19], v[36:37], v[18:19]
	v_pk_mul_f32 v[20:21], v[34:35], v[20:21]
	v_pk_mul_f32 v[28:29], v[22:23], v[48:49]
	v_pk_mul_f32 v[32:33], v[24:25], v[50:51]
	v_pk_mul_f32 v[34:35], v[18:19], v[48:49]
	v_pk_mul_f32 v[36:37], v[20:21], v[50:51]
	v_pk_fma_f32 v[20:21], v[20:21], v[30:31], v[32:33] neg_lo:[0,0,1] neg_hi:[0,0,1]
	v_pk_fma_f32 v[18:19], v[18:19], v[26:27], v[28:29] neg_lo:[0,0,1] neg_hi:[0,0,1]
	v_pk_fma_f32 v[24:25], v[24:25], v[30:31], v[36:37]
	v_pk_fma_f32 v[22:23], v[22:23], v[26:27], v[34:35]
	v_cvt_pk_bf16_f32 v18, v18, v19
	v_cvt_pk_bf16_f32 v19, v20, v21
	v_cvt_pk_bf16_f32 v20, v22, v23
	v_cvt_pk_bf16_f32 v21, v24, v25
	global_store_dwordx2 v[38:39], v[18:19], off offset:128 nt
	global_store_dwordx2 v[38:39], v[20:21], off offset:160 nt
	global_load_dwordx4 v[18:21], v[144:145], off
	v_pk_mul_f32 v[24:25], v[14:15], v[14:15]
	v_pk_mul_f32 v[22:23], v[16:17], v[16:17]
	v_mul_f32_e32 v24, v11, v11
	v_fmac_f32_e32 v25, v14, v14
	v_mul_f32_e32 v26, v7, v7
	v_pk_fma_f32 v[42:43], v[10:11], v[10:11], v[24:25] op_sel_hi:[1,1,0]
	v_mul_f32_e32 v38, v13, v13
	v_pk_fma_f32 v[26:27], v[6:7], v[6:7], v[26:27] op_sel_hi:[1,1,0]
	v_add_f32_e32 v22, v22, v25
	v_pk_fma_f32 v[24:25], v[12:13], v[12:13], v[42:43]
	v_mul_f32_e32 v40, v9, v9
	v_pk_fma_f32 v[26:27], v[8:9], v[8:9], v[26:27]
	v_pk_add_f32 v[24:25], v[38:39], v[24:25] op_sel_hi:[0,1]
	v_pk_add_f32 v[26:27], v[40:41], v[26:27] op_sel_hi:[0,1]
	v_fmamk_f32 v25, v79, 0x3b800000, v174
	v_mov_b32_e32 v30, v3
	v_and_b32_e32 v31, 0xffff0000, v70
	v_mul_f32_e32 v27, 0x4b800000, v25
	v_cmp_gt_f32_e32 vcc, s83, v25
	v_mov_b32_e32 v28, v2
	v_lshlrev_b32_e32 v29, 16, v70
	v_and_b32_e32 v39, 0xffff0000, v68
	v_lshlrev_b32_e32 v40, 16, v69
	v_pk_mul_f32 v[42:43], v[30:31], v[30:31]
	v_cndmask_b32_e32 v30, v25, v27, vcc
	v_mov_b32_e32 v36, v17
	v_lshlrev_b32_e32 v37, 16, v68
	v_and_b32_e32 v41, 0xffff0000, v69
	v_mul_f32_e32 v23, v39, v39
	v_mul_f32_e32 v38, v40, v40
	v_pk_fma_f32 v[42:43], v[28:29], v[28:29], v[42:43]
	v_rsq_f32_e32 v28, v30
	v_mov_b32_e32 v32, v4
	v_lshlrev_b32_e32 v33, 16, v71
	v_mul_f32_e32 v44, v41, v41
	v_pk_fma_f32 v[22:23], v[36:37], v[36:37], v[22:23]
	v_mov_b32_e32 v25, v38
	v_mov_b32_e32 v34, v5
	v_and_b32_e32 v35, 0xffff0000, v71
	v_mov_b32_e32 v27, v44
	v_pk_fma_f32 v[42:43], v[32:33], v[32:33], v[42:43]
	v_pk_add_f32 v[22:23], v[22:23], v[24:25]
	v_pk_fma_f32 v[24:25], v[34:35], v[34:35], v[42:43]
	v_pk_add_f32 v[22:23], v[22:23], v[26:27]
	v_mov_b32_e32 v30, v29
	v_pk_add_f32 v[22:23], v[24:25], v[22:23]
	v_mul_f32_e32 v24, 0x45800000, v28
	v_cndmask_b32_e32 v26, v28, v24, vcc
	v_mul_f32_e32 v24, v26, v26
	v_fmac_f32_e32 v23, v22, v24
	ds_bpermute_b32 v22, v178, v23
	v_mov_b32_e32 v38, v37
	v_mov_b32_e32 v34, v33
	s_waitcnt lgkmcnt(0)
	v_add_f32_e32 v24, v23, v22
	ds_bpermute_b32 v25, v177, v24
	v_lshl_add_u64 v[22:23], v[66:67], 3, s[62:63]
	s_waitcnt lgkmcnt(0)
	v_add_f32_e32 v24, v24, v25
	v_fmamk_f32 v24, v24, 0x3c2aaaab, v174
	v_mul_f32_e32 v25, 0x4b800000, v24
	v_cmp_gt_f32_e32 vcc, s83, v24
	s_waitcnt vmcnt(0)
	v_pk_mov_b32 v[42:43], v[18:19], v[20:21] op_sel:[1,0]
	v_cndmask_b32_e32 v24, v24, v25, vcc
	v_rsq_f32_e32 v27, v24
	v_mad_u64_u32 v[24:25], s[12:13], v22, s69, v[146:147]
	v_mad_i32_i24 v25, v23, s69, v25
	v_lshl_add_u64 v[22:23], v[24:25], 0, v[142:143]
	v_mul_f32_e32 v24, 0x45800000, v27
	v_cndmask_b32_e32 v24, v27, v24, vcc
	v_mul_f32_e32 v26, v26, v24
	v_pk_mul_f32 v[14:15], v[14:15], v[26:27] op_sel_hi:[1,0]
	v_pk_mul_f32 v[16:17], v[16:17], v[26:27] op_sel_hi:[1,0]
	v_mov_b32_e32 v20, v43
	v_mov_b32_e32 v19, v42
	v_pk_mul_f32 v[16:17], v[20:21], v[16:17]
	v_pk_mul_f32 v[14:15], v[18:19], v[14:15]
	v_pk_mul_f32 v[10:11], v[10:11], v[26:27] op_sel_hi:[1,0]
	v_cvt_pk_bf16_f32 v14, v14, v15
	v_cvt_pk_bf16_f32 v15, v16, v17
	global_store_dwordx2 v[22:23], v[14:15], off nt
	global_load_dwordx4 v[14:17], v[144:145], off offset:64
	v_pk_mul_f32 v[12:13], v[12:13], v[26:27] op_sel_hi:[1,0]
	v_pk_mul_f32 v[6:7], v[6:7], v[26:27] op_sel_hi:[1,0]
	v_pk_mul_f32 v[8:9], v[8:9], v[26:27] op_sel_hi:[1,0]
	v_cmp_gt_i32_e32 vcc, s70, v66
	v_pk_mul_f32 v[2:3], v[2:3], v[26:27] op_sel_hi:[1,0]
	v_pk_mul_f32 v[4:5], v[4:5], v[26:27] op_sel_hi:[1,0]
	v_pk_mul_f32 v[20:21], v[30:31], v[24:25] op_sel_hi:[1,0]
	v_pk_mul_f32 v[26:27], v[38:39], v[24:25] op_sel_hi:[1,0]
	s_waitcnt vmcnt(0)
	v_pk_mov_b32 v[18:19], v[14:15], v[16:17] op_sel:[1,0]
	s_nop 0
	v_mov_b32_e32 v16, v19
	v_mov_b32_e32 v15, v18
	v_pk_mul_f32 v[12:13], v[16:17], v[12:13]
	v_pk_mul_f32 v[10:11], v[14:15], v[10:11]
	v_pk_mul_f32 v[18:19], v[34:35], v[24:25] op_sel_hi:[1,0]
	v_cvt_pk_bf16_f32 v10, v10, v11
	v_cvt_pk_bf16_f32 v11, v12, v13
	global_store_dwordx2 v[22:23], v[10:11], off offset:32 nt
	global_load_dwordx4 v[10:13], v[144:145], off offset:128
	v_pk_mul_f32 v[24:25], v[40:41], v[24:25] op_sel_hi:[1,0]
	s_waitcnt vmcnt(0)
	v_pk_mov_b32 v[14:15], v[10:11], v[12:13] op_sel:[1,0]
	s_nop 0
	v_mov_b32_e32 v12, v15
	v_mov_b32_e32 v11, v14
	v_pk_mul_f32 v[8:9], v[8:9], v[12:13]
	v_pk_mul_f32 v[6:7], v[6:7], v[10:11]
	v_cndmask_b32_e32 v10, v175, v176, vcc
	v_cvt_pk_bf16_f32 v6, v6, v7
	v_cvt_pk_bf16_f32 v7, v8, v9
	global_store_dwordx2 v[22:23], v[6:7], off offset:64 nt
	global_load_dwordx4 v[6:9], v[144:145], off offset:192
	v_and_b32_e32 v10, v10, v66
	v_lshlrev_b32_e32 v134, 4, v10
	v_lshl_add_u64 v[10:11], v[134:135], 0, v[140:141]
	v_lshl_add_u64 v[14:15], v[10:11], 3, s[44:45]
	s_and_b64 vcc, exec, s[6:7]
	s_mov_b64 s[6:7], -1
	s_waitcnt vmcnt(0)
	v_pk_mov_b32 v[10:11], v[6:7], v[8:9] op_sel:[1,0]
	s_nop 0
	v_mov_b32_e32 v8, v11
	v_mov_b32_e32 v7, v10
	v_pk_mul_f32 v[4:5], v[4:5], v[8:9]
	v_pk_mul_f32 v[2:3], v[2:3], v[6:7]
	s_nop 0
	v_cvt_pk_bf16_f32 v2, v2, v3
	v_cvt_pk_bf16_f32 v3, v4, v5
	global_store_dwordx2 v[22:23], v[2:3], off offset:96 nt
	global_load_dwordx4 v[2:5], v[144:145], off offset:256
	s_nop 0
	global_load_dwordx4 v[6:9], v[144:145], off offset:320
	global_load_dwordx4 v[10:13], v[14:15], off
	s_nop 0
	global_load_dwordx4 v[14:17], v[14:15], off offset:16
	s_waitcnt vmcnt(3)
	v_pk_mov_b32 v[28:29], v[2:3], v[4:5] op_sel:[1,0]
	s_waitcnt vmcnt(2)
	v_pk_mov_b32 v[30:31], v[6:7], v[8:9] op_sel:[1,0]
	s_waitcnt vmcnt(1)
	v_mov_b32_e32 v32, v11
	v_mov_b32_e32 v8, v31
	v_mov_b32_e32 v7, v30
	v_mov_b32_e32 v33, v13
	s_waitcnt vmcnt(0)
	v_mov_b32_e32 v34, v15
	v_mov_b32_e32 v35, v17
	v_mov_b32_e32 v3, v28
	v_mov_b32_e32 v4, v29
	v_pk_mul_f32 v[8:9], v[24:25], v[8:9]
	v_pk_mul_f32 v[6:7], v[26:27], v[6:7]
	v_mov_b32_e32 v15, v16
	v_mov_b32_e32 v11, v12
	v_pk_mul_f32 v[2:3], v[20:21], v[2:3]
	v_pk_mul_f32 v[4:5], v[18:19], v[4:5]
	v_pk_mul_f32 v[12:13], v[6:7], v[32:33]
	v_pk_mul_f32 v[16:17], v[8:9], v[34:35]
	v_pk_mul_f32 v[18:19], v[2:3], v[32:33]
	v_pk_mul_f32 v[20:21], v[4:5], v[34:35]
	v_pk_fma_f32 v[4:5], v[4:5], v[14:15], v[16:17] neg_lo:[0,0,1] neg_hi:[0,0,1]
	v_pk_fma_f32 v[2:3], v[2:3], v[10:11], v[12:13] neg_lo:[0,0,1] neg_hi:[0,0,1]
	v_pk_fma_f32 v[8:9], v[8:9], v[14:15], v[20:21]
	v_pk_fma_f32 v[6:7], v[6:7], v[10:11], v[18:19]
	v_cvt_pk_bf16_f32 v2, v2, v3
	v_cvt_pk_bf16_f32 v3, v4, v5
	v_cvt_pk_bf16_f32 v4, v6, v7
	v_cvt_pk_bf16_f32 v5, v8, v9
	global_store_dwordx2 v[22:23], v[2:3], off offset:128 nt
	global_store_dwordx2 v[22:23], v[4:5], off offset:160 nt
	s_cbranch_vccnz .LBB0_586
	s_andn2_b64 vcc, exec, s[96:97]
	s_cbranch_vccnz .LBB0_585
	s_barrier
	s_branch .LBB0_585

.LBB0_627:
	s_lshl_b32 s0, s15, 8
	v_mov_b32_e32 v162, v1
	v_mov_b32_e32 v130, v148
	s_or_b32 s0, s0, s67
	s_nop 0
	v_lshl_add_u32 v144, v130, 2, s0
	v_ashrrev_i32_e32 v145, 31, v144
	v_lshl_add_u64 v[130:131], v[144:145], 2, s[40:41]
	global_load_dwordx4 v[130:133], v[130:131], off
	s_lshl_b32 s0, s14, 8
	s_add_i32 s0, s0, s65
	v_and_b32_e32 v153, 63, v162
	v_add_u32_e32 v138, 0xffffc000, v144
	v_add_u32_e32 v159, s0, v162
	v_lshrrev_b32_e32 v138, 9, v138
	v_and_b32_e32 v163, 0xffc, v144
	v_lshlrev_b32_e32 v155, 12, v153
	v_cmp_lt_i32_e32 vcc, s81, v144
	v_and_b32_e32 v158, 0x7ffff8, v138
	v_ashrrev_i32_e32 v154, 6, v159
	v_or3_b32 v138, v163, v155, s82
	s_and_saveexec_b64 s[0:1], vcc
	s_xor_b64 s[0:1], exec, s[0:1]
	v_add_u32_e32 v140, v158, v154
	v_ashrrev_i32_e32 v141, 31, v140
	v_lshlrev_b64 v[140:141], 18, v[140:141]
	v_lshl_add_u64 v[146:147], v[140:141], 0, v[138:139]
	s_or_saveexec_b64 s[0:1], s[0:1]
	v_ashrrev_i32_e32 v140, 10, v144
	v_and_b32_e32 v161, -8, v140
	v_and_b32_e32 v160, 0x1ffc, v144
	s_xor_b64 exec, exec, s[0:1]
	v_add_u32_e32 v140, v161, v154
	v_ashrrev_i32_e32 v141, 31, v140
	v_lshlrev_b64 v[146:147], 19, v[140:141]
	v_lshl_or_b32 v140, v153, 13, v146
	v_or_b32_e32 v146, v140, v160
	s_or_b64 exec, exec, s[0:1]
	v_add_u32_e32 v140, 16, v162
	v_and_b32_e32 v145, 63, v140
	v_mov_b64_e32 v[140:141], s[64:65]
	s_waitcnt vmcnt(0)
	v_pk_fma_f32 v[130:131], v[130:131], s[62:63], v[140:141] op_sel_hi:[1,0,0]
	v_pk_fma_f32 v[132:133], v[132:133], s[62:63], v[140:141] op_sel_hi:[1,0,0]
	v_mul_f32_e32 v142, 0x4b800000, v130
	v_cmp_gt_f32_e64 s[0:1], s82, v130
	v_cmp_gt_f32_e64 s[8:9], s82, v131
	v_mul_f32_e32 v140, 0x4b800000, v132
	v_cndmask_b32_e64 v130, v130, v142, s[0:1]
	v_mul_f32_e32 v142, 0x4b800000, v131
	v_cmp_gt_f32_e64 s[10:11], s82, v132
	v_cndmask_b32_e64 v131, v131, v142, s[8:9]
	v_cmp_gt_f32_e64 s[14:15], s82, v133
	v_cndmask_b32_e64 v132, v132, v140, s[10:11]
	v_mul_f32_e32 v140, 0x4b800000, v133
	v_rsq_f32_e32 v130, v130
	v_rsq_f32_e32 v131, v131
	v_cndmask_b32_e64 v133, v133, v140, s[14:15]
	v_rsq_f32_e32 v132, v132
	v_rsq_f32_e32 v133, v133
	v_pk_mul_f32 v[140:141], v[130:131], s[66:67] op_sel_hi:[1,0]
	v_lshlrev_b32_e32 v156, 12, v145
	v_cndmask_b32_e64 v131, v131, v141, s[8:9]
	v_cndmask_b32_e64 v130, v130, v140, s[0:1]
	v_pk_mul_f32 v[140:141], v[132:133], s[66:67] op_sel_hi:[1,0]
	v_pk_mul_f32 v[126:127], v[126:127], v[130:131]
	v_cndmask_b32_e64 v133, v133, v141, s[14:15]
	v_cndmask_b32_e64 v132, v132, v140, s[10:11]
	v_pk_mul_f32 v[128:129], v[128:129], v[132:133]
	v_lshl_add_u64 v[140:141], v[146:147], 1, s[46:47]
	v_cvt_pk_bf16_f32 v126, v126, v127
	v_cvt_pk_bf16_f32 v127, v128, v129
	global_store_dwordx2 v[140:141], v[126:127], off nt
	v_add_u32_e32 v126, 16, v159
	v_ashrrev_i32_e32 v147, 6, v126
	v_or3_b32 v126, v163, v156, s82
	s_and_saveexec_b64 s[0:1], vcc
	s_xor_b64 s[0:1], exec, s[0:1]
	v_add_u32_e32 v128, v158, v147
	v_ashrrev_i32_e32 v129, 31, v128
	v_lshlrev_b64 v[128:129], 18, v[128:129]
	v_mov_b32_e32 v127, v139
	v_lshl_add_u64 v[128:129], v[128:129], 0, v[126:127]
	s_andn2_saveexec_b64 s[0:1], s[0:1]
	v_add_u32_e32 v128, v161, v147
	v_ashrrev_i32_e32 v129, 31, v128
	v_lshlrev_b64 v[128:129], 19, v[128:129]
	v_lshl_or_b32 v127, v145, 13, v128
	v_or_b32_e32 v128, v127, v160
	s_or_b64 exec, exec, s[0:1]
	v_pk_mul_f32 v[124:125], v[124:125], v[132:133]
	v_pk_mul_f32 v[122:123], v[122:123], v[130:131]
	v_xor_b32_e32 v146, 32, v153
	v_lshl_add_u64 v[128:129], v[128:129], 1, s[46:47]
	v_cvt_pk_bf16_f32 v122, v122, v123
	v_cvt_pk_bf16_f32 v123, v124, v125
	global_store_dwordx2 v[128:129], v[122:123], off nt
	v_add_u32_e32 v122, 32, v159
	v_lshlrev_b32_e32 v157, 12, v146
	v_ashrrev_i32_e32 v129, 6, v122
	v_or3_b32 v122, v163, v157, s82
	s_and_saveexec_b64 s[0:1], vcc
	s_xor_b64 s[0:1], exec, s[0:1]
	v_add_u32_e32 v124, v158, v129
	v_ashrrev_i32_e32 v125, 31, v124
	v_lshlrev_b64 v[124:125], 18, v[124:125]
	v_mov_b32_e32 v123, v139
	v_lshl_add_u64 v[124:125], v[124:125], 0, v[122:123]
	s_andn2_saveexec_b64 s[0:1], s[0:1]
	v_add_u32_e32 v124, v161, v129
	v_ashrrev_i32_e32 v125, 31, v124
	v_lshlrev_b64 v[124:125], 19, v[124:125]
	v_lshl_or_b32 v123, v146, 13, v124
	v_or_b32_e32 v124, v123, v160
	s_or_b64 exec, exec, s[0:1]
	v_add_u32_e32 v123, 48, v162
	v_pk_mul_f32 v[120:121], v[120:121], v[132:133]
	v_pk_mul_f32 v[118:119], v[118:119], v[130:131]
	v_and_b32_e32 v128, 63, v123
	v_lshl_add_u64 v[124:125], v[124:125], 1, s[46:47]
	v_cvt_pk_bf16_f32 v118, v118, v119
	v_cvt_pk_bf16_f32 v119, v120, v121
	global_store_dwordx2 v[124:125], v[118:119], off nt
	v_add_u32_e32 v118, 48, v159
	v_lshlrev_b32_e32 v125, 12, v128
	v_ashrrev_i32_e32 v124, 6, v118
	v_or3_b32 v118, v163, v125, s82
	s_and_saveexec_b64 s[0:1], vcc
	s_xor_b64 s[0:1], exec, s[0:1]
	v_add_u32_e32 v120, v158, v124
	v_ashrrev_i32_e32 v121, 31, v120
	v_lshlrev_b64 v[120:121], 18, v[120:121]
	v_mov_b32_e32 v119, v139
	v_lshl_add_u64 v[120:121], v[120:121], 0, v[118:119]
	s_andn2_saveexec_b64 s[0:1], s[0:1]
	v_add_u32_e32 v120, v161, v124
	v_ashrrev_i32_e32 v121, 31, v120
	v_lshlrev_b64 v[120:121], 19, v[120:121]
	v_lshl_or_b32 v119, v128, 13, v120
	v_or_b32_e32 v120, v119, v160
	s_or_b64 exec, exec, s[0:1]
	v_pk_mul_f32 v[112:113], v[112:113], v[132:133]
	v_pk_mul_f32 v[110:111], v[110:111], v[130:131]
	v_lshl_add_u64 v[120:121], v[120:121], 1, s[46:47]
	v_cvt_pk_bf16_f32 v110, v110, v111
	v_cvt_pk_bf16_f32 v111, v112, v113
	global_store_dwordx2 v[120:121], v[110:111], off nt
	v_add_u32_e32 v110, 0x80, v159
	v_ashrrev_i32_e32 v113, 6, v110
	s_and_saveexec_b64 s[0:1], vcc
	s_xor_b64 s[0:1], exec, s[0:1]
	v_add_u32_e32 v110, v158, v113
	v_ashrrev_i32_e32 v111, 31, v110
	v_lshlrev_b64 v[110:111], 18, v[110:111]
	v_lshl_add_u64 v[110:111], v[110:111], 0, v[138:139]
	s_andn2_saveexec_b64 s[0:1], s[0:1]
	v_add_u32_e32 v110, v161, v113
	v_ashrrev_i32_e32 v111, 31, v110
	v_lshlrev_b64 v[110:111], 19, v[110:111]
	v_lshl_or_b32 v110, v153, 13, v110
	v_or_b32_e32 v110, v110, v160
	s_or_b64 exec, exec, s[0:1]
	v_pk_mul_f32 v[116:117], v[116:117], v[132:133]
	v_pk_mul_f32 v[114:115], v[114:115], v[130:131]
	v_lshl_add_u64 v[110:111], v[110:111], 1, s[46:47]
	v_cvt_pk_bf16_f32 v114, v114, v115
	v_cvt_pk_bf16_f32 v115, v116, v117
	global_store_dwordx2 v[110:111], v[114:115], off nt
	v_add_u32_e32 v110, 0x90, v159
	v_ashrrev_i32_e32 v112, 6, v110
	s_and_saveexec_b64 s[0:1], vcc
	s_xor_b64 s[0:1], exec, s[0:1]
	v_add_u32_e32 v110, v158, v112
	v_ashrrev_i32_e32 v111, 31, v110
	v_lshlrev_b64 v[110:111], 18, v[110:111]
	v_mov_b32_e32 v127, v139
	v_lshl_add_u64 v[110:111], v[110:111], 0, v[126:127]
	s_andn2_saveexec_b64 s[0:1], s[0:1]
	v_add_u32_e32 v110, v161, v112
	v_ashrrev_i32_e32 v111, 31, v110
	v_lshlrev_b64 v[110:111], 19, v[110:111]
	v_lshl_or_b32 v110, v145, 13, v110
	v_or_b32_e32 v110, v110, v160
	s_or_b64 exec, exec, s[0:1]
	v_pk_mul_f32 v[108:109], v[108:109], v[132:133]
	v_pk_mul_f32 v[106:107], v[106:107], v[130:131]
	v_lshl_add_u64 v[110:111], v[110:111], 1, s[46:47]
	v_cvt_pk_bf16_f32 v106, v106, v107
	v_cvt_pk_bf16_f32 v107, v108, v109
	global_store_dwordx2 v[110:111], v[106:107], off nt
	v_add_u32_e32 v106, 0xa0, v159
	v_ashrrev_i32_e32 v108, 6, v106
	s_and_saveexec_b64 s[0:1], vcc
	s_xor_b64 s[0:1], exec, s[0:1]
	v_add_u32_e32 v106, v158, v108
	v_ashrrev_i32_e32 v107, 31, v106
	v_lshlrev_b64 v[106:107], 18, v[106:107]
	v_mov_b32_e32 v123, v139
	v_lshl_add_u64 v[106:107], v[106:107], 0, v[122:123]
	s_andn2_saveexec_b64 s[0:1], s[0:1]
	v_add_u32_e32 v106, v161, v108
	v_ashrrev_i32_e32 v107, 31, v106
	v_lshlrev_b64 v[106:107], 19, v[106:107]
	v_lshl_or_b32 v106, v146, 13, v106
	v_or_b32_e32 v106, v106, v160
	s_or_b64 exec, exec, s[0:1]
	v_pk_mul_f32 v[104:105], v[104:105], v[132:133]
	v_pk_mul_f32 v[102:103], v[102:103], v[130:131]
	v_lshl_add_u64 v[106:107], v[106:107], 1, s[46:47]
	v_cvt_pk_bf16_f32 v102, v102, v103
	v_cvt_pk_bf16_f32 v103, v104, v105
	global_store_dwordx2 v[106:107], v[102:103], off nt
	v_add_u32_e32 v102, 0xb0, v159
	v_ashrrev_i32_e32 v106, 6, v102
	s_and_saveexec_b64 s[0:1], vcc
	s_xor_b64 s[0:1], exec, s[0:1]
	v_add_u32_e32 v102, v158, v106
	v_ashrrev_i32_e32 v103, 31, v102
	v_lshlrev_b64 v[102:103], 18, v[102:103]
	v_mov_b32_e32 v119, v139
	v_lshl_add_u64 v[102:103], v[102:103], 0, v[118:119]
	s_andn2_saveexec_b64 s[0:1], s[0:1]
	v_add_u32_e32 v102, v161, v106
	v_ashrrev_i32_e32 v103, 31, v102
	v_lshlrev_b64 v[102:103], 19, v[102:103]
	v_lshl_or_b32 v102, v128, 13, v102
	v_or_b32_e32 v102, v102, v160
	s_or_b64 exec, exec, s[0:1]
	v_pk_mul_f32 v[100:101], v[100:101], v[132:133]
	v_pk_mul_f32 v[98:99], v[98:99], v[130:131]
	v_add_u32_e32 v104, 16, v144
	v_lshl_add_u64 v[102:103], v[102:103], 1, s[46:47]
	v_cvt_pk_bf16_f32 v98, v98, v99
	v_cvt_pk_bf16_f32 v99, v100, v101
	v_ashrrev_i32_e32 v105, 31, v104
	global_store_dwordx2 v[102:103], v[98:99], off nt
	v_lshl_add_u64 v[98:99], v[104:105], 2, s[40:41]
	global_load_dwordx4 v[98:101], v[98:99], off
	v_add_u32_e32 v102, 0xffffc010, v144
	v_lshrrev_b32_e32 v102, 9, v102
	v_and_b32_e32 v109, 0xffc, v104
	v_cmp_lt_i32_e32 vcc, s81, v104
	v_and_b32_e32 v105, 0x7ffff8, v102
	v_or3_b32 v138, v109, v155, s82
	s_and_saveexec_b64 s[0:1], vcc
	s_xor_b64 s[0:1], exec, s[0:1]
	v_add_u32_e32 v102, v105, v154
	v_ashrrev_i32_e32 v103, 31, v102
	v_lshlrev_b64 v[102:103], 18, v[102:103]
	v_lshl_add_u64 v[102:103], v[102:103], 0, v[138:139]
	s_or_saveexec_b64 s[0:1], s[0:1]
	v_ashrrev_i32_e32 v107, 10, v104
	v_and_b32_e32 v107, -8, v107
	v_and_b32_e32 v104, 0x1ffc, v104
	s_xor_b64 exec, exec, s[0:1]
	v_add_u32_e32 v102, v107, v154
	v_ashrrev_i32_e32 v103, 31, v102
	v_lshlrev_b64 v[102:103], 19, v[102:103]
	v_lshl_or_b32 v102, v153, 13, v102
	v_or_b32_e32 v102, v102, v104
	s_or_b64 exec, exec, s[0:1]
	v_mov_b64_e32 v[110:111], s[64:65]
	s_waitcnt vmcnt(0)
	v_pk_fma_f32 v[98:99], v[98:99], s[62:63], v[110:111] op_sel_hi:[1,0,0]
	v_pk_fma_f32 v[100:101], v[100:101], s[62:63], v[110:111] op_sel_hi:[1,0,0]
	v_mul_f32_e32 v114, 0x4b800000, v98
	v_cmp_gt_f32_e64 s[0:1], s82, v98
	v_cmp_gt_f32_e64 s[8:9], s82, v99
	v_mul_f32_e32 v110, 0x4b800000, v100
	v_cndmask_b32_e64 v98, v98, v114, s[0:1]
	v_mul_f32_e32 v114, 0x4b800000, v99
	v_cmp_gt_f32_e64 s[10:11], s82, v100
	v_cndmask_b32_e64 v99, v99, v114, s[8:9]
	v_cmp_gt_f32_e64 s[14:15], s82, v101
	v_cndmask_b32_e64 v100, v100, v110, s[10:11]
	v_mul_f32_e32 v110, 0x4b800000, v101
	v_rsq_f32_e32 v98, v98
	v_rsq_f32_e32 v99, v99
	v_cndmask_b32_e64 v101, v101, v110, s[14:15]
	v_rsq_f32_e32 v100, v100
	v_rsq_f32_e32 v101, v101
	v_pk_mul_f32 v[110:111], v[98:99], s[66:67] op_sel_hi:[1,0]
	v_lshl_add_u64 v[102:103], v[102:103], 1, s[46:47]
	v_cndmask_b32_e64 v99, v99, v111, s[8:9]
	v_cndmask_b32_e64 v98, v98, v110, s[0:1]
	v_pk_mul_f32 v[110:111], v[100:101], s[66:67] op_sel_hi:[1,0]
	v_pk_mul_f32 v[94:95], v[94:95], v[98:99]
	v_cndmask_b32_e64 v101, v101, v111, s[14:15]
	v_cndmask_b32_e64 v100, v100, v110, s[10:11]
	v_pk_mul_f32 v[96:97], v[96:97], v[100:101]
	v_cvt_pk_bf16_f32 v94, v94, v95
	v_cvt_pk_bf16_f32 v95, v96, v97
	global_store_dwordx2 v[102:103], v[94:95], off nt
	v_or3_b32 v94, v109, v156, s82
	s_and_saveexec_b64 s[0:1], vcc
	s_xor_b64 s[0:1], exec, s[0:1]
	v_add_u32_e32 v96, v105, v147
	v_ashrrev_i32_e32 v97, 31, v96
	v_lshlrev_b64 v[96:97], 18, v[96:97]
	v_mov_b32_e32 v95, v139
	v_lshl_add_u64 v[96:97], v[96:97], 0, v[94:95]
	s_andn2_saveexec_b64 s[0:1], s[0:1]
	v_add_u32_e32 v96, v107, v147
	v_ashrrev_i32_e32 v97, 31, v96
	v_lshlrev_b64 v[96:97], 19, v[96:97]
	v_lshl_or_b32 v95, v145, 13, v96
	v_or_b32_e32 v96, v95, v104
	s_or_b64 exec, exec, s[0:1]
	v_pk_mul_f32 v[92:93], v[92:93], v[100:101]
	v_pk_mul_f32 v[90:91], v[90:91], v[98:99]
	v_lshl_add_u64 v[96:97], v[96:97], 1, s[46:47]
	v_cvt_pk_bf16_f32 v90, v90, v91
	v_cvt_pk_bf16_f32 v91, v92, v93
	global_store_dwordx2 v[96:97], v[90:91], off nt
	v_or3_b32 v90, v109, v157, s82
	s_and_saveexec_b64 s[0:1], vcc
	s_xor_b64 s[0:1], exec, s[0:1]
	v_add_u32_e32 v92, v105, v129
	v_ashrrev_i32_e32 v93, 31, v92
	v_lshlrev_b64 v[92:93], 18, v[92:93]
	v_mov_b32_e32 v91, v139
	v_lshl_add_u64 v[92:93], v[92:93], 0, v[90:91]
	s_andn2_saveexec_b64 s[0:1], s[0:1]
	v_add_u32_e32 v92, v107, v129
	v_ashrrev_i32_e32 v93, 31, v92
	v_lshlrev_b64 v[92:93], 19, v[92:93]
	v_lshl_or_b32 v91, v146, 13, v92
	v_or_b32_e32 v92, v91, v104
	s_or_b64 exec, exec, s[0:1]
	v_pk_mul_f32 v[88:89], v[88:89], v[100:101]
	v_pk_mul_f32 v[86:87], v[86:87], v[98:99]
	v_lshl_add_u64 v[92:93], v[92:93], 1, s[46:47]
	v_cvt_pk_bf16_f32 v86, v86, v87
	v_cvt_pk_bf16_f32 v87, v88, v89
	global_store_dwordx2 v[92:93], v[86:87], off nt
	v_or3_b32 v86, v109, v125, s82
	s_and_saveexec_b64 s[0:1], vcc
	s_xor_b64 s[0:1], exec, s[0:1]
	v_add_u32_e32 v88, v105, v124
	v_ashrrev_i32_e32 v89, 31, v88
	v_lshlrev_b64 v[88:89], 18, v[88:89]
	v_mov_b32_e32 v87, v139
	v_lshl_add_u64 v[88:89], v[88:89], 0, v[86:87]
	s_andn2_saveexec_b64 s[0:1], s[0:1]
	v_add_u32_e32 v88, v107, v124
	v_ashrrev_i32_e32 v89, 31, v88
	v_lshlrev_b64 v[88:89], 19, v[88:89]
	v_lshl_or_b32 v87, v128, 13, v88
	v_or_b32_e32 v88, v87, v104
	s_or_b64 exec, exec, s[0:1]
	v_pk_mul_f32 v[80:81], v[80:81], v[100:101]
	v_pk_mul_f32 v[78:79], v[78:79], v[98:99]
	v_lshl_add_u64 v[88:89], v[88:89], 1, s[46:47]
	v_cvt_pk_bf16_f32 v78, v78, v79
	v_cvt_pk_bf16_f32 v79, v80, v81
	global_store_dwordx2 v[88:89], v[78:79], off nt
	s_and_saveexec_b64 s[0:1], vcc
	s_xor_b64 s[0:1], exec, s[0:1]
	v_add_u32_e32 v78, v105, v113
	v_ashrrev_i32_e32 v79, 31, v78
	v_lshlrev_b64 v[78:79], 18, v[78:79]
	v_lshl_add_u64 v[78:79], v[78:79], 0, v[138:139]
	s_andn2_saveexec_b64 s[0:1], s[0:1]
	v_add_u32_e32 v78, v107, v113
	v_ashrrev_i32_e32 v79, 31, v78
	v_lshlrev_b64 v[78:79], 19, v[78:79]
	v_lshl_or_b32 v78, v153, 13, v78
	v_or_b32_e32 v78, v78, v104
	s_or_b64 exec, exec, s[0:1]
	v_pk_mul_f32 v[80:81], v[84:85], v[100:101]
	v_pk_mul_f32 v[82:83], v[82:83], v[98:99]
	v_lshl_add_u64 v[78:79], v[78:79], 1, s[46:47]
	v_cvt_pk_bf16_f32 v82, v82, v83
	v_cvt_pk_bf16_f32 v83, v80, v81
	global_store_dwordx2 v[78:79], v[82:83], off nt
	s_and_saveexec_b64 s[0:1], vcc
	s_xor_b64 s[0:1], exec, s[0:1]
	v_add_u32_e32 v78, v105, v112
	v_ashrrev_i32_e32 v79, 31, v78
	v_lshlrev_b64 v[78:79], 18, v[78:79]
	v_mov_b32_e32 v95, v139
	v_lshl_add_u64 v[78:79], v[78:79], 0, v[94:95]
	s_andn2_saveexec_b64 s[0:1], s[0:1]
	v_add_u32_e32 v78, v107, v112
	v_ashrrev_i32_e32 v79, 31, v78
	v_lshlrev_b64 v[78:79], 19, v[78:79]
	v_lshl_or_b32 v78, v145, 13, v78
	v_or_b32_e32 v78, v78, v104
	s_or_b64 exec, exec, s[0:1]
	v_pk_mul_f32 v[76:77], v[76:77], v[100:101]
	v_pk_mul_f32 v[74:75], v[74:75], v[98:99]
	v_lshl_add_u64 v[78:79], v[78:79], 1, s[46:47]
	v_cvt_pk_bf16_f32 v74, v74, v75
	v_cvt_pk_bf16_f32 v75, v76, v77
	global_store_dwordx2 v[78:79], v[74:75], off nt
	s_and_saveexec_b64 s[0:1], vcc
	s_xor_b64 s[0:1], exec, s[0:1]
	v_add_u32_e32 v74, v105, v108
	v_ashrrev_i32_e32 v75, 31, v74
	v_lshlrev_b64 v[74:75], 18, v[74:75]
	v_mov_b32_e32 v91, v139
	v_lshl_add_u64 v[74:75], v[74:75], 0, v[90:91]
	s_andn2_saveexec_b64 s[0:1], s[0:1]
	v_add_u32_e32 v74, v107, v108
	v_ashrrev_i32_e32 v75, 31, v74
	v_lshlrev_b64 v[74:75], 19, v[74:75]
	v_lshl_or_b32 v74, v146, 13, v74
	v_or_b32_e32 v74, v74, v104
	s_or_b64 exec, exec, s[0:1]
	v_pk_mul_f32 v[72:73], v[72:73], v[100:101]
	v_pk_mul_f32 v[70:71], v[70:71], v[98:99]
	v_lshl_add_u64 v[74:75], v[74:75], 1, s[46:47]
	v_cvt_pk_bf16_f32 v70, v70, v71
	v_cvt_pk_bf16_f32 v71, v72, v73
	global_store_dwordx2 v[74:75], v[70:71], off nt
	s_and_saveexec_b64 s[0:1], vcc
	s_xor_b64 s[0:1], exec, s[0:1]
	v_add_u32_e32 v70, v105, v106
	v_ashrrev_i32_e32 v71, 31, v70
	v_lshlrev_b64 v[70:71], 18, v[70:71]
	v_mov_b32_e32 v87, v139
	v_lshl_add_u64 v[70:71], v[70:71], 0, v[86:87]
	s_andn2_saveexec_b64 s[0:1], s[0:1]
	v_add_u32_e32 v70, v107, v106
	v_ashrrev_i32_e32 v71, 31, v70
	v_lshlrev_b64 v[70:71], 19, v[70:71]
	v_lshl_or_b32 v70, v128, 13, v70
	v_or_b32_e32 v70, v70, v104
	s_or_b64 exec, exec, s[0:1]
	v_pk_mul_f32 v[68:69], v[68:69], v[100:101]
	v_pk_mul_f32 v[66:67], v[66:67], v[98:99]
	v_add_u32_e32 v72, 0x80, v144
	v_lshl_add_u64 v[70:71], v[70:71], 1, s[46:47]
	v_cvt_pk_bf16_f32 v66, v66, v67
	v_cvt_pk_bf16_f32 v67, v68, v69
	v_ashrrev_i32_e32 v73, 31, v72
	global_store_dwordx2 v[70:71], v[66:67], off nt
	v_lshl_add_u64 v[66:67], v[72:73], 2, s[40:41]
	global_load_dwordx4 v[66:69], v[66:67], off
	v_add_u32_e32 v70, 0xffffc080, v144
	v_lshrrev_b32_e32 v70, 9, v70
	v_and_b32_e32 v75, 0xffc, v72
	v_cmp_lt_i32_e32 vcc, s81, v72
	v_and_b32_e32 v73, 0x7ffff8, v70
	v_or3_b32 v138, v75, v155, s82
	s_and_saveexec_b64 s[0:1], vcc
	s_xor_b64 s[0:1], exec, s[0:1]
	v_add_u32_e32 v70, v73, v154
	v_ashrrev_i32_e32 v71, 31, v70
	v_lshlrev_b64 v[70:71], 18, v[70:71]
	v_lshl_add_u64 v[70:71], v[70:71], 0, v[138:139]
	s_or_saveexec_b64 s[0:1], s[0:1]
	v_ashrrev_i32_e32 v74, 10, v72
	v_and_b32_e32 v74, -8, v74
	v_and_b32_e32 v72, 0x1ffc, v72
	s_xor_b64 exec, exec, s[0:1]
	v_add_u32_e32 v70, v74, v154
	v_ashrrev_i32_e32 v71, 31, v70
	v_lshlrev_b64 v[70:71], 19, v[70:71]
	v_lshl_or_b32 v70, v153, 13, v70
	v_or_b32_e32 v70, v70, v72
	s_or_b64 exec, exec, s[0:1]
	v_mov_b64_e32 v[76:77], s[64:65]
	s_waitcnt vmcnt(0)
	v_pk_fma_f32 v[66:67], v[66:67], s[62:63], v[76:77] op_sel_hi:[1,0,0]
	v_pk_fma_f32 v[68:69], v[68:69], s[62:63], v[76:77] op_sel_hi:[1,0,0]
	v_mul_f32_e32 v78, 0x4b800000, v66
	v_cmp_gt_f32_e64 s[0:1], s82, v66
	v_cmp_gt_f32_e64 s[8:9], s82, v67
	v_mul_f32_e32 v76, 0x4b800000, v68
	v_cndmask_b32_e64 v66, v66, v78, s[0:1]
	v_mul_f32_e32 v78, 0x4b800000, v67
	v_cmp_gt_f32_e64 s[10:11], s82, v68
	v_cndmask_b32_e64 v67, v67, v78, s[8:9]
	v_cmp_gt_f32_e64 s[14:15], s82, v69
	v_cndmask_b32_e64 v68, v68, v76, s[10:11]
	v_mul_f32_e32 v76, 0x4b800000, v69
	v_rsq_f32_e32 v66, v66
	v_rsq_f32_e32 v67, v67
	v_cndmask_b32_e64 v69, v69, v76, s[14:15]
	v_rsq_f32_e32 v68, v68
	v_rsq_f32_e32 v69, v69
	v_pk_mul_f32 v[76:77], v[66:67], s[66:67] op_sel_hi:[1,0]
	v_lshl_add_u64 v[70:71], v[70:71], 1, s[46:47]
	v_cndmask_b32_e64 v67, v67, v77, s[8:9]
	v_cndmask_b32_e64 v66, v66, v76, s[0:1]
	v_pk_mul_f32 v[76:77], v[68:69], s[66:67] op_sel_hi:[1,0]
	v_pk_mul_f32 v[62:63], v[62:63], v[66:67]
	v_cndmask_b32_e64 v69, v69, v77, s[14:15]
	v_cndmask_b32_e64 v68, v68, v76, s[10:11]
	v_pk_mul_f32 v[64:65], v[64:65], v[68:69]
	v_cvt_pk_bf16_f32 v62, v62, v63
	v_cvt_pk_bf16_f32 v63, v64, v65
	global_store_dwordx2 v[70:71], v[62:63], off nt
	v_or3_b32 v62, v75, v156, s82
	s_and_saveexec_b64 s[0:1], vcc
	s_xor_b64 s[0:1], exec, s[0:1]
	v_add_u32_e32 v64, v73, v147
	v_ashrrev_i32_e32 v65, 31, v64
	v_lshlrev_b64 v[64:65], 18, v[64:65]
	v_mov_b32_e32 v63, v139
	v_lshl_add_u64 v[64:65], v[64:65], 0, v[62:63]
	s_andn2_saveexec_b64 s[0:1], s[0:1]
	v_add_u32_e32 v64, v74, v147
	v_ashrrev_i32_e32 v65, 31, v64
	v_lshlrev_b64 v[64:65], 19, v[64:65]
	v_lshl_or_b32 v63, v145, 13, v64
	v_or_b32_e32 v64, v63, v72
	s_or_b64 exec, exec, s[0:1]
	v_pk_mul_f32 v[60:61], v[60:61], v[68:69]
	v_pk_mul_f32 v[58:59], v[58:59], v[66:67]
	v_lshl_add_u64 v[64:65], v[64:65], 1, s[46:47]
	v_cvt_pk_bf16_f32 v58, v58, v59
	v_cvt_pk_bf16_f32 v59, v60, v61
	global_store_dwordx2 v[64:65], v[58:59], off nt
	v_or3_b32 v58, v75, v157, s82
	s_and_saveexec_b64 s[0:1], vcc
	s_xor_b64 s[0:1], exec, s[0:1]
	v_add_u32_e32 v60, v73, v129
	v_ashrrev_i32_e32 v61, 31, v60
	v_lshlrev_b64 v[60:61], 18, v[60:61]
	v_mov_b32_e32 v59, v139
	v_lshl_add_u64 v[60:61], v[60:61], 0, v[58:59]
	s_andn2_saveexec_b64 s[0:1], s[0:1]
	v_add_u32_e32 v60, v74, v129
	v_ashrrev_i32_e32 v61, 31, v60
	v_lshlrev_b64 v[60:61], 19, v[60:61]
	v_lshl_or_b32 v59, v146, 13, v60
	v_or_b32_e32 v60, v59, v72
	s_or_b64 exec, exec, s[0:1]
	v_pk_mul_f32 v[56:57], v[56:57], v[68:69]
	v_pk_mul_f32 v[54:55], v[54:55], v[66:67]
	v_lshl_add_u64 v[60:61], v[60:61], 1, s[46:47]
	v_cvt_pk_bf16_f32 v54, v54, v55
	v_cvt_pk_bf16_f32 v55, v56, v57
	global_store_dwordx2 v[60:61], v[54:55], off nt
	v_or3_b32 v54, v75, v125, s82
	s_and_saveexec_b64 s[0:1], vcc
	s_xor_b64 s[0:1], exec, s[0:1]
	v_add_u32_e32 v56, v73, v124
	v_ashrrev_i32_e32 v57, 31, v56
	v_lshlrev_b64 v[56:57], 18, v[56:57]
	v_mov_b32_e32 v55, v139
	v_lshl_add_u64 v[56:57], v[56:57], 0, v[54:55]
	s_andn2_saveexec_b64 s[0:1], s[0:1]
	v_add_u32_e32 v56, v74, v124
	v_ashrrev_i32_e32 v57, 31, v56
	v_lshlrev_b64 v[56:57], 19, v[56:57]
	v_lshl_or_b32 v55, v128, 13, v56
	v_or_b32_e32 v56, v55, v72
	s_or_b64 exec, exec, s[0:1]
	v_pk_mul_f32 v[48:49], v[48:49], v[68:69]
	v_pk_mul_f32 v[46:47], v[46:47], v[66:67]
	v_lshl_add_u64 v[56:57], v[56:57], 1, s[46:47]
	v_cvt_pk_bf16_f32 v46, v46, v47
	v_cvt_pk_bf16_f32 v47, v48, v49
	global_store_dwordx2 v[56:57], v[46:47], off nt
	s_and_saveexec_b64 s[0:1], vcc
	s_xor_b64 s[0:1], exec, s[0:1]
	v_add_u32_e32 v46, v73, v113
	v_ashrrev_i32_e32 v47, 31, v46
	v_lshlrev_b64 v[46:47], 18, v[46:47]
	v_lshl_add_u64 v[46:47], v[46:47], 0, v[138:139]
	s_andn2_saveexec_b64 s[0:1], s[0:1]
	v_add_u32_e32 v46, v74, v113
	v_ashrrev_i32_e32 v47, 31, v46
	v_lshlrev_b64 v[46:47], 19, v[46:47]
	v_lshl_or_b32 v46, v153, 13, v46
	v_or_b32_e32 v46, v46, v72
	s_or_b64 exec, exec, s[0:1]
	v_pk_mul_f32 v[48:49], v[52:53], v[68:69]
	v_pk_mul_f32 v[50:51], v[50:51], v[66:67]
	v_lshl_add_u64 v[46:47], v[46:47], 1, s[46:47]
	v_cvt_pk_bf16_f32 v50, v50, v51
	v_cvt_pk_bf16_f32 v51, v48, v49
	global_store_dwordx2 v[46:47], v[50:51], off nt
	s_and_saveexec_b64 s[0:1], vcc
	s_xor_b64 s[0:1], exec, s[0:1]
	v_add_u32_e32 v46, v73, v112
	v_ashrrev_i32_e32 v47, 31, v46
	v_lshlrev_b64 v[46:47], 18, v[46:47]
	v_mov_b32_e32 v63, v139
	v_lshl_add_u64 v[46:47], v[46:47], 0, v[62:63]
	s_andn2_saveexec_b64 s[0:1], s[0:1]
	v_add_u32_e32 v46, v74, v112
	v_ashrrev_i32_e32 v47, 31, v46
	v_lshlrev_b64 v[46:47], 19, v[46:47]
	v_lshl_or_b32 v46, v145, 13, v46
	v_or_b32_e32 v46, v46, v72
	s_or_b64 exec, exec, s[0:1]
	v_pk_mul_f32 v[44:45], v[44:45], v[68:69]
	v_pk_mul_f32 v[42:43], v[42:43], v[66:67]
	v_lshl_add_u64 v[46:47], v[46:47], 1, s[46:47]
	v_cvt_pk_bf16_f32 v42, v42, v43
	v_cvt_pk_bf16_f32 v43, v44, v45
	global_store_dwordx2 v[46:47], v[42:43], off nt
	s_and_saveexec_b64 s[0:1], vcc
	s_xor_b64 s[0:1], exec, s[0:1]
	v_add_u32_e32 v42, v73, v108
	v_ashrrev_i32_e32 v43, 31, v42
	v_lshlrev_b64 v[42:43], 18, v[42:43]
	v_mov_b32_e32 v59, v139
	v_lshl_add_u64 v[42:43], v[42:43], 0, v[58:59]
	s_andn2_saveexec_b64 s[0:1], s[0:1]
	v_add_u32_e32 v42, v74, v108
	v_ashrrev_i32_e32 v43, 31, v42
	v_lshlrev_b64 v[42:43], 19, v[42:43]
	v_lshl_or_b32 v42, v146, 13, v42
	v_or_b32_e32 v42, v42, v72
	s_or_b64 exec, exec, s[0:1]
	v_pk_mul_f32 v[40:41], v[40:41], v[68:69]
	v_pk_mul_f32 v[38:39], v[38:39], v[66:67]
	v_lshl_add_u64 v[42:43], v[42:43], 1, s[46:47]
	v_cvt_pk_bf16_f32 v38, v38, v39
	v_cvt_pk_bf16_f32 v39, v40, v41
	global_store_dwordx2 v[42:43], v[38:39], off nt
	s_and_saveexec_b64 s[0:1], vcc
	s_xor_b64 s[0:1], exec, s[0:1]
	v_add_u32_e32 v38, v73, v106
	v_ashrrev_i32_e32 v39, 31, v38
	v_lshlrev_b64 v[38:39], 18, v[38:39]
	v_mov_b32_e32 v55, v139
	v_lshl_add_u64 v[38:39], v[38:39], 0, v[54:55]
	s_andn2_saveexec_b64 s[0:1], s[0:1]
	v_add_u32_e32 v38, v74, v106
	v_ashrrev_i32_e32 v39, 31, v38
	v_lshlrev_b64 v[38:39], 19, v[38:39]
	v_lshl_or_b32 v38, v128, 13, v38
	v_or_b32_e32 v38, v38, v72
	s_or_b64 exec, exec, s[0:1]
	v_pk_mul_f32 v[36:37], v[36:37], v[68:69]
	v_pk_mul_f32 v[34:35], v[34:35], v[66:67]
	v_add_u32_e32 v40, 0x90, v144
	v_lshl_add_u64 v[38:39], v[38:39], 1, s[46:47]
	v_cvt_pk_bf16_f32 v34, v34, v35
	v_cvt_pk_bf16_f32 v35, v36, v37
	v_ashrrev_i32_e32 v41, 31, v40
	global_store_dwordx2 v[38:39], v[34:35], off nt
	v_lshl_add_u64 v[34:35], v[40:41], 2, s[40:41]
	global_load_dwordx4 v[34:37], v[34:35], off
	v_add_u32_e32 v38, 0xffffc090, v144
	v_lshrrev_b32_e32 v38, 9, v38
	v_and_b32_e32 v43, 0xffc, v40
	v_cmp_lt_i32_e32 vcc, s81, v40
	v_and_b32_e32 v41, 0x7ffff8, v38
	v_or3_b32 v138, v43, v155, s82
	s_and_saveexec_b64 s[0:1], vcc
	s_xor_b64 s[0:1], exec, s[0:1]
	v_add_u32_e32 v38, v41, v154
	v_ashrrev_i32_e32 v39, 31, v38
	v_lshlrev_b64 v[38:39], 18, v[38:39]
	v_lshl_add_u64 v[38:39], v[38:39], 0, v[138:139]
	s_or_saveexec_b64 s[0:1], s[0:1]
	v_ashrrev_i32_e32 v42, 10, v40
	v_and_b32_e32 v42, -8, v42
	v_and_b32_e32 v40, 0x1ffc, v40
	s_xor_b64 exec, exec, s[0:1]
	v_add_u32_e32 v38, v42, v154
	v_ashrrev_i32_e32 v39, 31, v38
	v_lshlrev_b64 v[38:39], 19, v[38:39]
	v_lshl_or_b32 v38, v153, 13, v38
	v_or_b32_e32 v38, v38, v40
	s_or_b64 exec, exec, s[0:1]
	v_mov_b64_e32 v[44:45], s[64:65]
	s_waitcnt vmcnt(0)
	v_pk_fma_f32 v[34:35], v[34:35], s[62:63], v[44:45] op_sel_hi:[1,0,0]
	v_pk_fma_f32 v[36:37], v[36:37], s[62:63], v[44:45] op_sel_hi:[1,0,0]
	v_mul_f32_e32 v46, 0x4b800000, v34
	v_cmp_gt_f32_e64 s[0:1], s82, v34
	v_cmp_gt_f32_e64 s[8:9], s82, v35
	v_mul_f32_e32 v44, 0x4b800000, v36
	v_cndmask_b32_e64 v34, v34, v46, s[0:1]
	v_mul_f32_e32 v46, 0x4b800000, v35
	v_cmp_gt_f32_e64 s[10:11], s82, v36
	v_cndmask_b32_e64 v35, v35, v46, s[8:9]
	v_cmp_gt_f32_e64 s[14:15], s82, v37
	v_cndmask_b32_e64 v36, v36, v44, s[10:11]
	v_mul_f32_e32 v44, 0x4b800000, v37
	v_rsq_f32_e32 v34, v34
	v_rsq_f32_e32 v35, v35
	v_cndmask_b32_e64 v37, v37, v44, s[14:15]
	v_rsq_f32_e32 v36, v36
	v_rsq_f32_e32 v37, v37
	v_pk_mul_f32 v[44:45], v[34:35], s[66:67] op_sel_hi:[1,0]
	v_lshl_add_u64 v[38:39], v[38:39], 1, s[46:47]
	v_cndmask_b32_e64 v35, v35, v45, s[8:9]
	v_cndmask_b32_e64 v34, v34, v44, s[0:1]
	v_pk_mul_f32 v[44:45], v[36:37], s[66:67] op_sel_hi:[1,0]
	v_pk_mul_f32 v[30:31], v[30:31], v[34:35]
	v_cndmask_b32_e64 v37, v37, v45, s[14:15]
	v_cndmask_b32_e64 v36, v36, v44, s[10:11]
	v_pk_mul_f32 v[32:33], v[32:33], v[36:37]
	v_cvt_pk_bf16_f32 v30, v30, v31
	v_cvt_pk_bf16_f32 v31, v32, v33
	global_store_dwordx2 v[38:39], v[30:31], off nt
	v_or3_b32 v30, v43, v156, s82
	s_and_saveexec_b64 s[0:1], vcc
	s_xor_b64 s[0:1], exec, s[0:1]
	v_add_u32_e32 v32, v41, v147
	v_ashrrev_i32_e32 v33, 31, v32
	v_lshlrev_b64 v[32:33], 18, v[32:33]
	v_mov_b32_e32 v31, v139
	v_lshl_add_u64 v[32:33], v[32:33], 0, v[30:31]
	s_andn2_saveexec_b64 s[0:1], s[0:1]
	v_add_u32_e32 v32, v42, v147
	v_ashrrev_i32_e32 v33, 31, v32
	v_lshlrev_b64 v[32:33], 19, v[32:33]
	v_lshl_or_b32 v31, v145, 13, v32
	v_or_b32_e32 v32, v31, v40
	s_or_b64 exec, exec, s[0:1]
	v_pk_mul_f32 v[28:29], v[28:29], v[36:37]
	v_pk_mul_f32 v[26:27], v[26:27], v[34:35]
	v_lshl_add_u64 v[32:33], v[32:33], 1, s[46:47]
	v_cvt_pk_bf16_f32 v26, v26, v27
	v_cvt_pk_bf16_f32 v27, v28, v29
	global_store_dwordx2 v[32:33], v[26:27], off nt
	v_or3_b32 v26, v43, v157, s82
	s_and_saveexec_b64 s[0:1], vcc
	s_xor_b64 s[0:1], exec, s[0:1]
	v_add_u32_e32 v28, v41, v129
	v_ashrrev_i32_e32 v29, 31, v28
	v_lshlrev_b64 v[28:29], 18, v[28:29]
	v_mov_b32_e32 v27, v139
	v_lshl_add_u64 v[28:29], v[28:29], 0, v[26:27]
	s_andn2_saveexec_b64 s[0:1], s[0:1]
	v_add_u32_e32 v28, v42, v129
	v_ashrrev_i32_e32 v29, 31, v28
	v_lshlrev_b64 v[28:29], 19, v[28:29]
	v_lshl_or_b32 v27, v146, 13, v28
	v_or_b32_e32 v28, v27, v40
	s_or_b64 exec, exec, s[0:1]
	v_pk_mul_f32 v[24:25], v[24:25], v[36:37]
	v_pk_mul_f32 v[22:23], v[22:23], v[34:35]
	v_lshl_add_u64 v[28:29], v[28:29], 1, s[46:47]
	v_cvt_pk_bf16_f32 v22, v22, v23
	v_cvt_pk_bf16_f32 v23, v24, v25
	global_store_dwordx2 v[28:29], v[22:23], off nt
	v_or3_b32 v22, v43, v125, s82
	s_and_saveexec_b64 s[0:1], vcc
	s_xor_b64 s[0:1], exec, s[0:1]
	v_add_u32_e32 v24, v41, v124
	v_ashrrev_i32_e32 v25, 31, v24
	v_lshlrev_b64 v[24:25], 18, v[24:25]
	v_mov_b32_e32 v23, v139
	v_lshl_add_u64 v[24:25], v[24:25], 0, v[22:23]
	s_andn2_saveexec_b64 s[0:1], s[0:1]
	v_add_u32_e32 v24, v42, v124
	v_ashrrev_i32_e32 v25, 31, v24
	v_lshlrev_b64 v[24:25], 19, v[24:25]
	v_lshl_or_b32 v23, v128, 13, v24
	v_or_b32_e32 v24, v23, v40
	s_or_b64 exec, exec, s[0:1]
	v_pk_mul_f32 v[16:17], v[16:17], v[36:37]
	v_pk_mul_f32 v[14:15], v[14:15], v[34:35]
	v_lshl_add_u64 v[24:25], v[24:25], 1, s[46:47]
	v_cvt_pk_bf16_f32 v14, v14, v15
	v_cvt_pk_bf16_f32 v15, v16, v17
	global_store_dwordx2 v[24:25], v[14:15], off nt
	s_and_saveexec_b64 s[0:1], vcc
	s_xor_b64 s[0:1], exec, s[0:1]
	v_add_u32_e32 v14, v41, v113
	v_ashrrev_i32_e32 v15, 31, v14
	v_lshlrev_b64 v[14:15], 18, v[14:15]
	v_lshl_add_u64 v[14:15], v[14:15], 0, v[138:139]
	s_andn2_saveexec_b64 s[0:1], s[0:1]
	v_add_u32_e32 v14, v42, v113
	v_ashrrev_i32_e32 v15, 31, v14
	v_lshlrev_b64 v[14:15], 19, v[14:15]
	v_lshl_or_b32 v14, v153, 13, v14
	v_or_b32_e32 v14, v14, v40
	s_or_b64 exec, exec, s[0:1]
	v_pk_mul_f32 v[16:17], v[20:21], v[36:37]
	v_pk_mul_f32 v[18:19], v[18:19], v[34:35]
	v_lshl_add_u64 v[14:15], v[14:15], 1, s[46:47]
	v_cvt_pk_bf16_f32 v18, v18, v19
	v_cvt_pk_bf16_f32 v19, v16, v17
	global_store_dwordx2 v[14:15], v[18:19], off nt
	s_and_saveexec_b64 s[0:1], vcc
	s_xor_b64 s[0:1], exec, s[0:1]
	v_add_u32_e32 v14, v41, v112
	v_ashrrev_i32_e32 v15, 31, v14
	v_lshlrev_b64 v[14:15], 18, v[14:15]
	v_mov_b32_e32 v31, v139
	v_lshl_add_u64 v[14:15], v[14:15], 0, v[30:31]
	s_andn2_saveexec_b64 s[0:1], s[0:1]
	v_add_u32_e32 v14, v42, v112
	v_ashrrev_i32_e32 v15, 31, v14
	v_lshlrev_b64 v[14:15], 19, v[14:15]
	v_lshl_or_b32 v14, v145, 13, v14
	v_or_b32_e32 v14, v14, v40
	s_or_b64 exec, exec, s[0:1]
	v_pk_mul_f32 v[12:13], v[12:13], v[36:37]
	v_pk_mul_f32 v[10:11], v[10:11], v[34:35]
	v_lshl_add_u64 v[14:15], v[14:15], 1, s[46:47]
	v_cvt_pk_bf16_f32 v10, v10, v11
	v_cvt_pk_bf16_f32 v11, v12, v13
	global_store_dwordx2 v[14:15], v[10:11], off nt
	s_and_saveexec_b64 s[0:1], vcc
	s_xor_b64 s[0:1], exec, s[0:1]
	v_add_u32_e32 v10, v41, v108
	v_ashrrev_i32_e32 v11, 31, v10
	v_lshlrev_b64 v[10:11], 18, v[10:11]
	v_mov_b32_e32 v27, v139
	v_lshl_add_u64 v[10:11], v[10:11], 0, v[26:27]
	s_andn2_saveexec_b64 s[0:1], s[0:1]
	v_add_u32_e32 v10, v42, v108
	v_ashrrev_i32_e32 v11, 31, v10
	v_lshlrev_b64 v[10:11], 19, v[10:11]
	v_lshl_or_b32 v10, v146, 13, v10
	v_or_b32_e32 v10, v10, v40
	s_or_b64 exec, exec, s[0:1]
	v_pk_mul_f32 v[8:9], v[8:9], v[36:37]
	v_pk_mul_f32 v[6:7], v[6:7], v[34:35]
	v_lshl_add_u64 v[10:11], v[10:11], 1, s[46:47]
	v_cvt_pk_bf16_f32 v6, v6, v7
	v_cvt_pk_bf16_f32 v7, v8, v9
	global_store_dwordx2 v[10:11], v[6:7], off nt
	s_and_saveexec_b64 s[0:1], vcc
	s_xor_b64 s[0:1], exec, s[0:1]
	v_add_u32_e32 v6, v41, v106
	v_ashrrev_i32_e32 v7, 31, v6
	v_lshlrev_b64 v[6:7], 18, v[6:7]
	v_mov_b32_e32 v23, v139
	v_lshl_add_u64 v[6:7], v[6:7], 0, v[22:23]
	s_andn2_saveexec_b64 s[0:1], s[0:1]
	v_add_u32_e32 v6, v42, v106
	v_ashrrev_i32_e32 v7, 31, v6
	v_lshlrev_b64 v[6:7], 19, v[6:7]
	v_lshl_or_b32 v6, v128, 13, v6
	v_or_b32_e32 v6, v6, v40
	s_or_b64 exec, exec, s[0:1]
	v_pk_mul_f32 v[4:5], v[4:5], v[36:37]
	v_pk_mul_f32 v[2:3], v[2:3], v[34:35]
	v_lshl_add_u64 v[6:7], v[6:7], 1, s[46:47]
	v_cvt_pk_bf16_f32 v2, v2, v3
	v_cvt_pk_bf16_f32 v3, v4, v5
	s_and_b64 vcc, exec, s[6:7]
	s_mov_b64 s[0:1], -1
	global_store_dwordx2 v[6:7], v[2:3], off nt
	s_cbranch_vccnz .LBB0_614
	s_andn2_b64 vcc, exec, s[50:51]
	s_cbranch_vccnz .LBB0_613
	s_barrier
	s_branch .LBB0_613
